# residual epilogues (out-proj, ff2): one s_barrier at the start of every 16-row group so the waves sharing residual rows issue their loads/stores together (on the one-barrier attention version)
# speedup vs baseline: 1.0149x; 1.0149x over previous
; #define WAIT_V0() asm volatile("s_waitcnt vmcnt(0)" ::: "memory")
; #define G_STAGE_A(Ap, buf, kt) do { const char* ab_ = (const char*)(Ap) + (size_t)(kt) * 128; \
;       _Pragma("unroll") for (int i = 0; i < 4; ++i) \
;         __builtin_amdgcn_global_load_lds((const unsigned*)(ab_ + soff[i]), (LDSP unsigned*)(G_SA(buf) + wid * 1024 + i * 8192), 16, 0, 0); } while (0)
; #define G_STAGE_B(Bp, buf, kt) do { const char* bb_ = (const char*)(Bp) + (size_t)(kt) * 128; \
;       _Pragma("unroll") for (int i = 0; i < 4; ++i) \
;         __builtin_amdgcn_global_load_lds((const unsigned*)(bb_ + soff[i]), (LDSP unsigned*)(G_SB(buf) + wid * 1024 + i * 8192), 16, 0, 0); } while (0)
; #define G_RDA(AF, buf, ks, mh) do { _Pragma("unroll") for (int m = 0; m < 4; ++m) AF[m] = *(const LDSP bf16x8*)(G_SA(buf) + aoff + ((mh) * 4 + m) * 2048 + (ks) * 1024); } while (0)
; #define G_RDB(BF, buf, ks) do { _Pragma("unroll") for (int n = 0; n < 4; ++n) BF[n] = *(const LDSP bf16x8*)(G_SB(buf) + boff + n * 2048 + (ks) * 1024); } while (0)
; #define G_SB0() __builtin_amdgcn_sched_barrier(0)
; template <int EK>
; DI void gemm_stream(const Params& p, int l, const bf16_t* __restrict__ A, const bf16_t* __restrict__ Bt, int M, int N, int K, ldsp_t shm) {
;     ...
;         for (int t = 0; t < nt; ++t) {
;             const int cur = t & 1;
;             G_RDA(Aa, cur, 0, 0); G_RDB(Bk0, cur, 0);
;             if (t + 1 < nt) G_STAGE_B(Bb, cur ^ 1, t + 1);
;             else if (has_next) G_STAGE_B(Bb2, cur ^ 1, 0);
;             G_SB0();
;             if (t > 0) G_MMA(Ab_, Bk1, 1);
;             G_SB0();
;             if (t + 1 < nt) G_STAGE_A(Ab, cur ^ 1, t + 1);
;             else if (has_next) G_STAGE_A(Ab2, cur ^ 1, 0);
;             G_RDA(Ab_, cur, 0, 1);
;             G_MMA(Aa, Bk0, 0); G_SB0();
;             G_RDA(Aa, cur, 1, 0); G_RDB(Bk1, cur, 1);
;             G_MMA(Ab_, Bk0, 1); G_SB0();
;             G_RDA(Ab_, cur, 1, 1);
;             G_MMA(Aa, Bk1, 0); G_SB0();
;             asm volatile("s_waitcnt lgkmcnt(0)" ::: "memory");
;             WAIT_V0(); __syncthreads();
;         }
;         G_MMA(Ab_, Bk1, 1);
.LBB0_137:
	v_add_u32_e32 v80, 0x12000, v218
	v_add_u32_e32 v84, 0x12800, v218
	v_add_u32_e32 v88, 0x13000, v218
	v_add_u32_e32 v92, 0x13800, v218
	ds_read_b128 v[80:83], v80
	ds_read_b128 v[84:87], v84
	ds_read_b128 v[88:91], v88
	ds_read_b128 v[92:95], v92
	s_setprio 1
	s_waitcnt lgkmcnt(0)
	v_mfma_f32_16x16x32_bf16 v[0:3], v[160:163], v[188:191], v[0:3]
	v_mfma_f32_16x16x32_bf16 v[4:7], v[164:167], v[188:191], v[4:7]
	v_mfma_f32_16x16x32_bf16 v[8:11], v[168:171], v[188:191], v[8:11]
	v_mfma_f32_16x16x32_bf16 v[12:15], v[172:175], v[188:191], v[12:15]
	v_mfma_f32_16x16x32_bf16 v[16:19], v[160:163], v[180:183], v[16:19]
	v_mfma_f32_16x16x32_bf16 v[20:23], v[164:167], v[180:183], v[20:23]
	v_mfma_f32_16x16x32_bf16 v[24:27], v[168:171], v[180:183], v[24:27]
	v_mfma_f32_16x16x32_bf16 v[28:31], v[172:175], v[180:183], v[28:31]
	v_mfma_f32_16x16x32_bf16 v[32:35], v[160:163], v[184:187], v[32:35]
	v_mfma_f32_16x16x32_bf16 v[36:39], v[164:167], v[184:187], v[36:39]
	v_mfma_f32_16x16x32_bf16 v[40:43], v[168:171], v[184:187], v[40:43]
	v_mfma_f32_16x16x32_bf16 v[44:47], v[172:175], v[184:187], v[44:47]
	v_mfma_f32_16x16x32_bf16 v[48:51], v[160:163], v[176:179], v[48:51]
	v_mfma_f32_16x16x32_bf16 v[52:55], v[164:167], v[176:179], v[52:55]
	v_mfma_f32_16x16x32_bf16 v[56:59], v[168:171], v[176:179], v[56:59]
	v_mfma_f32_16x16x32_bf16 v[60:63], v[172:175], v[176:179], v[60:63]
	s_setprio 0
	v_add_u32_e32 v144, 0x10400, v218
	v_add_u32_e32 v148, 0x10c00, v218
	v_add_u32_e32 v152, 0x11400, v218
	v_add_u32_e32 v156, 0x11c00, v218
	v_add_u32_e32 v176, 0x18400, v219
	v_add_u32_e32 v180, 0x18c00, v219
	v_add_u32_e32 v184, 0x19400, v219
	v_add_u32_e32 v188, 0x19c00, v219
	ds_read_b128 v[144:147], v144
	ds_read_b128 v[148:151], v148
	ds_read_b128 v[152:155], v152
	ds_read_b128 v[156:159], v156
	ds_read_b128 v[176:179], v176
	ds_read_b128 v[180:183], v180
	ds_read_b128 v[184:187], v184
	ds_read_b128 v[188:191], v188
	s_setprio 1
	v_mfma_f32_16x16x32_bf16 v[194:197], v[160:163], v[80:83], v[140:143]
	v_mfma_f32_16x16x32_bf16 v[198:201], v[164:167], v[80:83], v[136:139]
	v_mfma_f32_16x16x32_bf16 v[204:207], v[168:171], v[80:83], v[132:135]
	v_mfma_f32_16x16x32_bf16 v[210:213], v[172:175], v[80:83], v[128:131]
	v_mfma_f32_16x16x32_bf16 v[214:217], v[160:163], v[84:87], v[124:127]
	v_mfma_f32_16x16x32_bf16 v[220:223], v[164:167], v[84:87], v[120:123]
	v_mfma_f32_16x16x32_bf16 v[224:227], v[168:171], v[84:87], v[116:119]
	v_mfma_f32_16x16x32_bf16 v[228:231], v[172:175], v[84:87], v[112:115]
	v_mfma_f32_16x16x32_bf16 v[232:235], v[160:163], v[88:91], v[108:111]
	v_mfma_f32_16x16x32_bf16 v[236:239], v[164:167], v[88:91], v[104:107]
	v_mfma_f32_16x16x32_bf16 v[240:243], v[168:171], v[88:91], v[100:103]
	v_mfma_f32_16x16x32_bf16 v[244:247], v[172:175], v[88:91], v[96:99]
	v_mfma_f32_16x16x32_bf16 v[160:163], v[160:163], v[92:95], v[64:67]
	v_mfma_f32_16x16x32_bf16 v[164:167], v[164:167], v[92:95], v[68:71]
	v_mfma_f32_16x16x32_bf16 v[168:171], v[168:171], v[92:95], v[72:75]
	v_mfma_f32_16x16x32_bf16 v[172:175], v[172:175], v[92:95], v[76:79]
	s_setprio 0
	v_add_u32_e32 v64, 0x12400, v218
	v_add_u32_e32 v68, 0x12c00, v218
	ds_read_b128 v[64:67], v64
	ds_read_b128 v[248:251], v68
	v_add_u32_e32 v68, 0x13400, v218
	v_add_u32_e32 v72, 0x13c00, v218
	ds_read_b128 v[68:71], v68
	ds_read_b128 v[72:75], v72
	s_setprio 1
	s_waitcnt lgkmcnt(0)
	v_mfma_f32_16x16x32_bf16 v[140:143], v[176:179], v[144:147], v[0:3]
	v_mfma_f32_16x16x32_bf16 v[136:139], v[180:183], v[144:147], v[4:7]
	v_mfma_f32_16x16x32_bf16 v[132:135], v[184:187], v[144:147], v[8:11]
	v_mfma_f32_16x16x32_bf16 v[128:131], v[188:191], v[144:147], v[12:15]
	v_mfma_f32_16x16x32_bf16 v[124:127], v[176:179], v[148:151], v[16:19]
	v_mfma_f32_16x16x32_bf16 v[120:123], v[180:183], v[148:151], v[20:23]
	v_mfma_f32_16x16x32_bf16 v[116:119], v[184:187], v[148:151], v[24:27]
	v_mfma_f32_16x16x32_bf16 v[112:115], v[188:191], v[148:151], v[28:31]
	v_mfma_f32_16x16x32_bf16 v[108:111], v[176:179], v[152:155], v[32:35]
	v_mfma_f32_16x16x32_bf16 v[104:107], v[180:183], v[152:155], v[36:39]
	v_mfma_f32_16x16x32_bf16 v[100:103], v[184:187], v[152:155], v[40:43]
	v_mfma_f32_16x16x32_bf16 v[96:99], v[188:191], v[152:155], v[44:47]
	v_mfma_f32_16x16x32_bf16 v[92:95], v[176:179], v[156:159], v[48:51]
	v_mfma_f32_16x16x32_bf16 v[88:91], v[180:183], v[156:159], v[52:55]
	v_mfma_f32_16x16x32_bf16 v[84:87], v[184:187], v[156:159], v[56:59]
	v_mfma_f32_16x16x32_bf16 v[80:83], v[188:191], v[156:159], v[60:63]
	s_setprio 0
	s_waitcnt lgkmcnt(0)
	s_waitcnt vmcnt(0)
	s_waitcnt vmcnt(0)
	s_barrier
; #define G_MMA(AF, BF, mh) do { __builtin_amdgcn_s_setprio(1); \
;             _Pragma("unroll") for (int m = 0; m < 4; ++m) _Pragma("unroll") for (int n = 0; n < 4; ++n) \
;                 acc[(mh) * 4 + m][n] = __builtin_amdgcn_mfma_f32_16x16x32_bf16(BF[n], AF[m], acc[(mh) * 4 + m][n], 0, 0, 0); \
;             __builtin_amdgcn_s_setprio(0); } while (0)
;     static DI void run(const f32x4 (&acc)[8][4], const TileCtx& tc, const Params& p, ldsp_t wb) {
;         constexpr int GI = EK == 1 ? 2 : 5;
;         const int cond = tc.brow < NLAT ? (tc.brow >> 12) : 4;
;         const float* gate = p.mod + ((size_t)tc.l * 5 + cond) * 6144 + GI * DM;
;         const int col0 = tc.bcol + tc.wc * 64 + tc.fq * 4;
;         const bool has_next = EK == 1 || tc.l + 1 < DEPTH;
;         const int ln = EK == 1 ? tc.l : (has_next ? tc.l + 1 : tc.l);
;         const float* gnx = (EK == 1 ? p.norm2_g : p.norm1_g) + (size_t)ln * DM + col0;
;         const float* scn = p.mod + ((size_t)ln * 5 + cond) * 6144 + (EK == 1 ? 4 : 1) * DM + col0;
;         float* ssp = p.ss + (size_t)(ln * 2 + (EK == 1 ? 1 : 0)) * NTOK * 16 + (tc.bcol >> 8) * 4 + tc.wc;
;         f32x4 gv[4], av[4];
; #pragma unroll
;         for (int n = 0; n < 4; ++n) {
;             gv[n] = *(const f32x4*)(gate + col0 + n * 16);
;             const f32x4 g1 = *(const f32x4*)(gnx + n * 16), s1 = *(const f32x4*)(scn + n * 16);
;             av[n] = g1 * (1.f + s1);
;         }
; #pragma unroll
;         for (int h = 0; h < 2; ++h) {
; #pragma unroll
;             for (int mm = 0; mm < 4; ++mm) { __builtin_amdgcn_sched_barrier(0);
;                 const int m = h * 4 + mm;
;                 const int row = tc.brow + tc.wr * 128 + m * 16 + tc.fr;
;                 float* xr = xrow_ptr(p, row) + col0;
;                 const float* xs = (EK == 1 && tc.l == 0) ? p.x + (size_t)row * DM + col0 : xr;
; template <int EK>
; DI void gemm_stream(const Params& p, int l, const bf16_t* __restrict__ A, const bf16_t* __restrict__ Bt, int M, int N, int K, ldsp_t shm) {
;     ...
;         G_MMA(Ab_, Bk1, 1);
	s_setprio 1
	v_mfma_f32_16x16x32_bf16 v[76:79], v[176:179], v[64:67], v[194:197]
	v_mfma_f32_16x16x32_bf16 v[198:201], v[180:183], v[64:67], v[198:201]
	v_mfma_f32_16x16x32_bf16 v[194:197], v[184:187], v[64:67], v[204:207]
	v_mfma_f32_16x16x32_bf16 v[64:67], v[188:191], v[64:67], v[210:213]
	v_mfma_f32_16x16x32_bf16 v[60:63], v[176:179], v[248:251], v[214:217]
	v_mfma_f32_16x16x32_bf16 v[56:59], v[180:183], v[248:251], v[220:223]
	v_mfma_f32_16x16x32_bf16 v[52:55], v[184:187], v[248:251], v[224:227]
	v_mfma_f32_16x16x32_bf16 v[48:51], v[188:191], v[248:251], v[228:231]
	v_mfma_f32_16x16x32_bf16 v[44:47], v[176:179], v[68:71], v[232:235]
	v_mfma_f32_16x16x32_bf16 v[40:43], v[180:183], v[68:71], v[236:239]
	v_mfma_f32_16x16x32_bf16 v[36:39], v[184:187], v[68:71], v[240:243]
	v_mfma_f32_16x16x32_bf16 v[32:35], v[188:191], v[68:71], v[244:247]
	v_mfma_f32_16x16x32_bf16 v[16:19], v[176:179], v[72:75], v[160:163]
	v_mfma_f32_16x16x32_bf16 v[12:15], v[180:183], v[72:75], v[164:167]
	v_mfma_f32_16x16x32_bf16 v[8:11], v[184:187], v[72:75], v[168:171]
	v_mfma_f32_16x16x32_bf16 v[0:3], v[188:191], v[72:75], v[172:175]
	s_setprio 0
	v_mov_b32_e32 v177, v252
	s_lshl_b32 s41, s88, 8
	s_min_i32 s6, s41, 0x4000
	s_ashr_i32 s6, s6, 12
	v_readlane_b32 s8, v255, 10
	s_lshl_b32 s38, s87, 8
	s_ashr_i32 s7, s6, 31
	s_mul_i32 s39, s8, 5
	s_add_u32 s6, s39, s6
	s_mul_hi_i32 s39, s8, 5
	v_ashrrev_i32_e32 v144, 6, v177
	s_addc_u32 s7, s39, s7
	v_mov_b64_e32 v[4:5], s[66:67]
	v_mov_b32_e32 v6, 0x6000
	v_and_b32_e32 v145, 3, v144
	s_mul_i32 s39, s7, 0x6000
	v_mad_u64_u32 v[4:5], s[6:7], s6, v6, v[4:5]
	v_lshrrev_b32_e32 v6, 2, v177
	v_lshlrev_b32_e32 v172, 6, v145
	v_and_b32_e32 v6, 12, v6
	v_or3_b32 v6, v6, s38, v172
	v_ashrrev_i32_e32 v7, 31, v6
	v_add_u32_e32 v5, s39, v5
	v_lshlrev_b64 v[150:151], 2, v[6:7]
	v_lshl_add_u64 v[4:5], v[4:5], 0, v[150:151]
	v_add_co_u32_e32 v20, vcc, s33, v4
	s_mov_b64 s[6:7], 0x4000
	s_nop 0
	v_addc_co_u32_e32 v21, vcc, 0, v5, vcc
	global_load_dwordx4 v[68:71], v[20:21], off
	v_lshl_add_u64 v[20:21], v[4:5], 0, s[6:7]
	s_movk_i32 s6, 0x2000
	v_lshl_add_u64 v[6:7], s[34:35], 0, v[150:151]
	global_load_dwordx4 v[72:75], v[20:21], off offset:64
	global_load_dwordx4 v[146:149], v[6:7], off
	global_load_dwordx4 v[152:155], v[20:21], off offset:128
	global_load_dwordx4 v[156:159], v[20:21], off offset:192
	v_add_co_u32_e32 v20, vcc, s6, v4
	s_mov_b64 s[6:7], 0x2000
	s_nop 0
	v_addc_co_u32_e32 v21, vcc, 0, v5, vcc
	global_load_dwordx4 v[164:167], v[6:7], off offset:64
	global_load_dwordx4 v[28:31], v[20:21], off
	global_load_dwordx4 v[178:181], v[6:7], off offset:128
	v_lshl_add_u64 v[4:5], v[4:5], 0, s[6:7]
	global_load_dwordx4 v[182:185], v[6:7], off offset:192
	global_load_dwordx4 v[24:27], v[4:5], off offset:64
	global_load_dwordx4 v[20:23], v[4:5], off offset:128
	s_nop 0
	global_load_dwordx4 v[4:7], v[4:5], off offset:192
	s_lshl_b32 s6, s87, 2
	v_xor_b32_e32 v230, 16, v202
	s_ashr_i32 s7, s6, 31
	v_cmp_lt_i32_e32 vcc, v230, v203
	s_lshl_b64 s[6:7], s[6:7], 2
	s_add_u32 s6, s31, s6
	v_cndmask_b32_e32 v160, v202, v230, vcc
	v_cmp_lt_i32_e32 vcc, v209, v203
	v_lshlrev_b32_e32 v170, 2, v160
	v_mov_b32_e32 v160, 0x10000
	v_cndmask_b32_e32 v171, v202, v209, vcc
	v_lshlrev_b32_e32 v192, 2, v145
	s_addc_u32 s7, s45, s7
	v_and_b32_e32 v175, 63, v177
	v_and_b32_e32 v173, 15, v177
	v_lshl_add_u32 v176, v144, 13, v160
	v_lshl_add_u64 v[144:145], s[6:7], 0, v[192:193]
	v_lshlrev_b32_e32 v171, 2, v171
	v_readlane_b32 s9, v255, 11
	s_waitcnt vmcnt(11)
	v_pk_add_f32 v[70:71], v[70:71], 1.0 op_sel_hi:[1,0]
	v_pk_add_f32 v[68:69], v[68:69], 1.0 op_sel_hi:[1,0]
	s_waitcnt vmcnt(10)
	v_pk_add_f32 v[74:75], v[74:75], 1.0 op_sel_hi:[1,0]
	v_pk_add_f32 v[72:73], v[72:73], 1.0 op_sel_hi:[1,0]
	s_waitcnt vmcnt(8)
	v_pk_add_f32 v[154:155], v[154:155], 1.0 op_sel_hi:[1,0]
	v_pk_add_f32 v[168:169], v[152:153], 1.0 op_sel_hi:[1,0]
	s_waitcnt vmcnt(7)
	v_pk_add_f32 v[186:187], v[158:159], 1.0 op_sel_hi:[1,0]
	v_pk_add_f32 v[188:189], v[156:157], 1.0 op_sel_hi:[1,0]
	v_pk_mul_f32 v[160:161], v[148:149], v[70:71]
	v_pk_mul_f32 v[162:163], v[146:147], v[68:69]
	s_waitcnt vmcnt(6)
	v_pk_mul_f32 v[156:157], v[166:167], v[74:75]
	v_pk_mul_f32 v[158:159], v[164:165], v[72:73]
	s_waitcnt vmcnt(4)
	v_pk_mul_f32 v[152:153], v[180:181], v[154:155]
	v_pk_mul_f32 v[154:155], v[178:179], v[168:169]
	s_waitcnt vmcnt(3)
	v_pk_mul_f32 v[146:147], v[184:185], v[186:187]
	v_pk_mul_f32 v[148:149], v[182:183], v[188:189]
	v_ashrrev_i32_e32 v68, 1, v177
	v_and_b32_e32 v174, 0xffffff80, v68
	v_add_u32_e32 v164, s41, v174
	v_or_b32_e32 v166, v164, v173
	v_cmp_gt_i32_e32 vcc, s33, v166
	v_add_u32_e32 v68, 0xffffc000, v166
	v_ashrrev_i32_e32 v167, 31, v166
	v_mov_b32_e32 v70, s71
	v_mov_b32_e32 v71, s55
	v_cndmask_b32_e32 v69, 0, v167, vcc
	v_cndmask_b32_e32 v68, v68, v166, vcc
	v_cndmask_b32_e32 v71, v70, v71, vcc
	v_mov_b32_e32 v70, s70
	v_mov_b32_e32 v72, s54
	v_cndmask_b32_e32 v70, v70, v72, vcc
	v_lshlrev_b64 v[68:69], 12, v[68:69]
	v_readlane_b32 s8, v254, 50
	v_lshl_add_u64 v[68:69], v[70:71], 0, v[68:69]
	v_lshlrev_b64 v[70:71], 12, v[166:167]
	v_readlane_b32 s9, v254, 51
	v_lshl_add_u64 v[168:169], v[68:69], 0, v[150:151]
	v_bfe_u32 v75, v177, 5, 1
	v_lshl_add_u64 v[70:71], s[8:9], 0, v[70:71]
	v_cndmask_b32_e64 v69, v69, v71, s[4:5]
	v_cndmask_b32_e64 v68, v68, v70, s[4:5]
	v_lshl_add_u64 v[72:73], v[68:69], 0, v[150:151]
	s_barrier
; DI unsigned pk2(float a, float b) { f32x2 v = {a, b}; bf2_t r = __builtin_convertvector(v, bf2_t); return __builtin_bit_cast(unsigned, r); }
;     static DI void run(const f32x4 (&acc)[8][4], const TileCtx& tc, const Params& p, ldsp_t wb) {
;     ...
;             for (int mm = 0; mm < 4; ++mm) { __builtin_amdgcn_sched_barrier(0);
;                 const int m = h * 4 + mm;
;                 const int row = tc.brow + tc.wr * 128 + m * 16 + tc.fr;
;                 float* xr = xrow_ptr(p, row) + col0;
;                 const float* xs = (EK == 1 && tc.l == 0) ? p.x + (size_t)row * DM + col0 : xr;
;                 float part = 0.f;
; #pragma unroll
;                 for (int n = 0; n < 4; ++n) {
;                     f32x4 xv = *(const f32x4*)(xs + n * 16);
;                     xv += gv[n] * acc[m][n];
;                     *(f32x4*)(xr + n * 16) = xv;
;                     if (has_next) {
;                         part += xv[0] * xv[0] + xv[1] * xv[1] + xv[2] * xv[2] + xv[3] * xv[3];
;                         const f32x4 hv = xv * av[n];
;                         u32x2 w; w[0] = pk2(hv[0], hv[1]); w[1] = pk2(hv[2], hv[3]);
;                         wave_put(wb, mm * 16 + tc.fr, n, tc.fq, w);
;                     }
;                 }
;                 if (has_next) {
;                     part += __shfl_xor(part, 16);
;                     part += __shfl_xor(part, 32);
;                     if (tc.fq == 0) ssp[(size_t)row * 16] = part;
;                 }
	global_load_dwordx4 v[68:71], v[72:73], off
	global_load_dwordx4 v[232:235], v[72:73], off offset:64
	global_load_dwordx4 v[236:239], v[72:73], off offset:128
	global_load_dwordx4 v[240:243], v[72:73], off offset:192
	v_cmp_gt_u32_e32 vcc, 16, v175
	v_readlane_b32 s10, v254, 52
	v_readlane_b32 s11, v254, 53
	v_readlane_b32 s12, v254, 54
	v_readlane_b32 s13, v254, 55
	v_readlane_b32 s14, v254, 56
	v_readlane_b32 s15, v254, 57
	v_readlane_b32 s16, v254, 58
	v_readlane_b32 s17, v254, 59
	v_readlane_b32 s18, v254, 60
	v_readlane_b32 s19, v254, 61
	v_readlane_b32 s20, v254, 62
	v_readlane_b32 s21, v254, 63
	v_readlane_b32 s22, v255, 0
	v_readlane_b32 s23, v255, 1
	s_waitcnt vmcnt(3)
	v_pk_fma_f32 v[68:69], v[140:141], v[28:29], v[68:69]
	s_nop 0
	v_mul_f32_e32 v74, v69, v69
	v_pk_fma_f32 v[70:71], v[142:143], v[30:31], v[70:71]
	v_fmac_f32_e32 v74, v68, v68
	v_fmac_f32_e32 v74, v70, v70
	global_store_dwordx4 v[168:169], v[68:71], off
	v_fmac_f32_e32 v74, v71, v71
	v_lshl_or_b32 v142, v173, 7, v176
	v_pk_mul_f32 v[70:71], v[160:161], v[70:71]
	v_pk_mul_f32 v[68:69], v[162:163], v[68:69]
	v_and_b32_e32 v143, 7, v177
	v_cvt_pk_bf16_f32 v68, v68, v69
	v_cvt_pk_bf16_f32 v69, v70, v71
	v_bitop3_b32 v70, v75, v177, 7 bitop3:0x78
	v_lshl_or_b32 v141, v70, 4, v142
	v_lshrrev_b32_e32 v70, 1, v177
	v_and_b32_e32 v140, 8, v70
	v_or_b32_e32 v70, v141, v140
	ds_write_b64 v70, v[68:69]
	s_nop 1
	s_waitcnt vmcnt(3)
	v_pk_fma_f32 v[68:69], v[136:137], v[24:25], v[232:233]
	s_nop 0
	v_mul_f32_e32 v136, v69, v69
	v_pk_fma_f32 v[70:71], v[138:139], v[26:27], v[234:235]
	v_fmac_f32_e32 v136, v68, v68
	v_fmac_f32_e32 v136, v70, v70
	global_store_dwordx4 v[168:169], v[68:71], off offset:64
	v_fmac_f32_e32 v136, v71, v71
	v_add_f32_e32 v74, v74, v136
	v_pk_mul_f32 v[70:71], v[156:157], v[70:71]
	v_pk_mul_f32 v[68:69], v[158:159], v[68:69]
	s_nop 0
	v_cvt_pk_bf16_f32 v68, v68, v69
	v_cvt_pk_bf16_f32 v69, v70, v71
	v_bitop3_b32 v70, v75, v143, 2 bitop3:0x36
	v_lshl_or_b32 v136, v70, 4, v142
	v_or_b32_e32 v70, v136, v140
	ds_write_b64 v70, v[68:69]
	s_nop 1
	s_waitcnt vmcnt(3)
	v_pk_fma_f32 v[68:69], v[132:133], v[20:21], v[236:237]
	s_nop 0
	v_mul_f32_e32 v132, v69, v69
	v_pk_fma_f32 v[70:71], v[134:135], v[22:23], v[238:239]
	v_fmac_f32_e32 v132, v68, v68
	v_fmac_f32_e32 v132, v70, v70
	global_store_dwordx4 v[168:169], v[68:71], off offset:128
	v_fmac_f32_e32 v132, v71, v71
	v_add_f32_e32 v74, v74, v132
	v_pk_mul_f32 v[70:71], v[152:153], v[70:71]
	v_pk_mul_f32 v[68:69], v[154:155], v[68:69]
	s_nop 0
	v_cvt_pk_bf16_f32 v68, v68, v69
	v_cvt_pk_bf16_f32 v69, v70, v71
	v_bitop3_b32 v70, v75, v143, 4 bitop3:0x36
	v_lshl_or_b32 v133, v70, 4, v142
	v_or_b32_e32 v70, v133, v140
	ds_write_b64 v70, v[68:69]
	s_nop 1
	s_waitcnt vmcnt(3)
	v_pk_fma_f32 v[68:69], v[128:129], v[4:5], v[240:241]
	s_nop 0
	v_mul_f32_e32 v72, v69, v69
	v_pk_fma_f32 v[70:71], v[130:131], v[6:7], v[242:243]
	v_fmac_f32_e32 v72, v68, v68
	v_fmac_f32_e32 v72, v70, v70
	global_store_dwordx4 v[168:169], v[68:71], off offset:192
	v_fmac_f32_e32 v72, v71, v71
	v_add_f32_e32 v72, v74, v72
	v_pk_mul_f32 v[70:71], v[146:147], v[70:71]
	v_pk_mul_f32 v[68:69], v[148:149], v[68:69]
	s_nop 0
	v_cvt_pk_bf16_f32 v68, v68, v69
	v_cvt_pk_bf16_f32 v69, v70, v71
	v_bitop3_b32 v70, v75, v143, 6 bitop3:0x36
	v_lshl_or_b32 v134, v70, 4, v142
	v_or_b32_e32 v70, v134, v140
	ds_write_b64 v70, v[68:69]
	ds_bpermute_b32 v68, v170, v72
	s_waitcnt lgkmcnt(0)
	v_add_f32_e32 v128, v72, v68
	ds_bpermute_b32 v129, v171, v128
	s_and_saveexec_b64 s[6:7], vcc
	s_cbranch_execz .LBB0_139
	v_lshlrev_b64 v[68:69], 6, v[166:167]
	s_waitcnt lgkmcnt(0)
	v_add_f32_e32 v70, v128, v129
	v_lshl_add_u64 v[68:69], v[144:145], 0, v[68:69]
	global_store_dword v[68:69], v70, off sc1
.LBB0_139:
	s_or_b64 exec, exec, s[6:7]
	v_or_b32_e32 v68, s41, v173
	v_add_u32_e32 v132, v174, v68
	v_add_u32_e32 v128, 16, v132
	v_cmp_gt_i32_e64 s[6:7], s33, v128
	v_add_u32_e32 v68, 0xffffc010, v132
	s_waitcnt lgkmcnt(0)
	v_ashrrev_i32_e32 v129, 31, v128
	v_mov_b32_e32 v70, s71
	v_mov_b32_e32 v71, s55
	v_cndmask_b32_e64 v69, 0, v129, s[6:7]
	v_cndmask_b32_e64 v68, v68, v128, s[6:7]
	v_cndmask_b32_e64 v71, v70, v71, s[6:7]
	v_mov_b32_e32 v70, s70
	v_mov_b32_e32 v72, s54
	v_cndmask_b32_e64 v70, v70, v72, s[6:7]
	v_lshlrev_b64 v[68:69], 12, v[68:69]
	v_readlane_b32 s8, v254, 50
	v_lshl_add_u64 v[68:69], v[70:71], 0, v[68:69]
	v_lshlrev_b64 v[70:71], 12, v[128:129]
	v_readlane_b32 s9, v254, 51
	v_lshl_add_u64 v[130:131], v[68:69], 0, v[150:151]
	v_readlane_b32 s10, v254, 52
	v_lshl_add_u64 v[70:71], s[8:9], 0, v[70:71]
	v_cndmask_b32_e64 v69, v69, v71, s[4:5]
	v_cndmask_b32_e64 v68, v68, v70, s[4:5]
	v_lshl_add_u64 v[72:73], v[68:69], 0, v[150:151]
	s_barrier
; DI unsigned pk2(float a, float b) { f32x2 v = {a, b}; bf2_t r = __builtin_convertvector(v, bf2_t); return __builtin_bit_cast(unsigned, r); }
;     static DI void run(const f32x4 (&acc)[8][4], const TileCtx& tc, const Params& p, ldsp_t wb) {
;     ...
;             for (int mm = 0; mm < 4; ++mm) { __builtin_amdgcn_sched_barrier(0);
;                 const int m = h * 4 + mm;
;                 const int row = tc.brow + tc.wr * 128 + m * 16 + tc.fr;
;                 float* xr = xrow_ptr(p, row) + col0;
;                 const float* xs = (EK == 1 && tc.l == 0) ? p.x + (size_t)row * DM + col0 : xr;
;                 float part = 0.f;
; #pragma unroll
;                 for (int n = 0; n < 4; ++n) {
;                     f32x4 xv = *(const f32x4*)(xs + n * 16);
;                     xv += gv[n] * acc[m][n];
;                     *(f32x4*)(xr + n * 16) = xv;
;                     if (has_next) {
;                         part += xv[0] * xv[0] + xv[1] * xv[1] + xv[2] * xv[2] + xv[3] * xv[3];
;                         const f32x4 hv = xv * av[n];
;                         u32x2 w; w[0] = pk2(hv[0], hv[1]); w[1] = pk2(hv[2], hv[3]);
;                         wave_put(wb, mm * 16 + tc.fr, n, tc.fq, w);
;                     }
;                 }
;                 if (has_next) {
;                     part += __shfl_xor(part, 16);
;                     part += __shfl_xor(part, 32);
;                     if (tc.fq == 0) ssp[(size_t)row * 16] = part;
;                 }
	global_load_dwordx4 v[68:71], v[72:73], off
	global_load_dwordx4 v[232:235], v[72:73], off offset:64
	global_load_dwordx4 v[236:239], v[72:73], off offset:128
	global_load_dwordx4 v[240:243], v[72:73], off offset:192
	v_readlane_b32 s11, v254, 53
	v_readlane_b32 s12, v254, 54
	v_readlane_b32 s13, v254, 55
	v_readlane_b32 s14, v254, 56
	v_readlane_b32 s15, v254, 57
	v_readlane_b32 s16, v254, 58
	v_readlane_b32 s17, v254, 59
	v_readlane_b32 s18, v254, 60
	v_readlane_b32 s19, v254, 61
	v_readlane_b32 s20, v254, 62
	v_readlane_b32 s21, v254, 63
	v_readlane_b32 s22, v255, 0
	v_readlane_b32 s23, v255, 1
	s_waitcnt vmcnt(3)
	v_pk_fma_f32 v[68:69], v[124:125], v[28:29], v[68:69]
	s_nop 0
	v_mul_f32_e32 v74, v69, v69
	v_pk_fma_f32 v[70:71], v[126:127], v[30:31], v[70:71]
	v_fmac_f32_e32 v74, v68, v68
	v_fmac_f32_e32 v74, v70, v70
	global_store_dwordx4 v[130:131], v[68:71], off
	v_fmac_f32_e32 v74, v71, v71
	v_add_u32_e32 v124, v141, v140
	v_pk_mul_f32 v[70:71], v[160:161], v[70:71]
	v_pk_mul_f32 v[68:69], v[162:163], v[68:69]
	s_nop 0
	v_cvt_pk_bf16_f32 v68, v68, v69
	v_cvt_pk_bf16_f32 v69, v70, v71
	ds_write_b64 v124, v[68:69] offset:2048
	s_nop 1
	s_waitcnt vmcnt(3)
	v_pk_fma_f32 v[68:69], v[120:121], v[24:25], v[232:233]
	s_nop 0
	v_mul_f32_e32 v75, v69, v69
	v_pk_fma_f32 v[70:71], v[122:123], v[26:27], v[234:235]
	v_fmac_f32_e32 v75, v68, v68
	v_fmac_f32_e32 v75, v70, v70
	global_store_dwordx4 v[130:131], v[68:71], off offset:64
	v_fmac_f32_e32 v75, v71, v71
	v_add_u32_e32 v120, v136, v140
	v_pk_mul_f32 v[70:71], v[156:157], v[70:71]
	v_pk_mul_f32 v[68:69], v[158:159], v[68:69]
	v_add_f32_e32 v74, v74, v75
	v_cvt_pk_bf16_f32 v68, v68, v69
	v_cvt_pk_bf16_f32 v69, v70, v71
	ds_write_b64 v120, v[68:69] offset:2048
	s_nop 1
	s_waitcnt vmcnt(3)
	v_pk_fma_f32 v[68:69], v[116:117], v[20:21], v[236:237]
	s_nop 0
	v_mul_f32_e32 v75, v69, v69
	v_pk_fma_f32 v[70:71], v[118:119], v[22:23], v[238:239]
	v_fmac_f32_e32 v75, v68, v68
	v_fmac_f32_e32 v75, v70, v70
	global_store_dwordx4 v[130:131], v[68:71], off offset:128
	v_fmac_f32_e32 v75, v71, v71
	v_add_u32_e32 v116, v133, v140
	v_pk_mul_f32 v[70:71], v[152:153], v[70:71]
	v_pk_mul_f32 v[68:69], v[154:155], v[68:69]
	v_add_f32_e32 v74, v74, v75
	v_cvt_pk_bf16_f32 v68, v68, v69
	v_cvt_pk_bf16_f32 v69, v70, v71
	ds_write_b64 v116, v[68:69] offset:2048
	s_nop 1
	v_add_u32_e32 v117, v134, v140
	s_waitcnt vmcnt(3)
	v_pk_fma_f32 v[68:69], v[112:113], v[4:5], v[240:241]
	s_nop 0
	v_mul_f32_e32 v72, v69, v69
	v_pk_fma_f32 v[70:71], v[114:115], v[6:7], v[242:243]
	v_fmac_f32_e32 v72, v68, v68
	v_fmac_f32_e32 v72, v70, v70
	global_store_dwordx4 v[130:131], v[68:71], off offset:192
	v_fmac_f32_e32 v72, v71, v71
	v_add_f32_e32 v72, v74, v72
	v_pk_mul_f32 v[70:71], v[146:147], v[70:71]
	v_pk_mul_f32 v[68:69], v[148:149], v[68:69]
	s_nop 0
	v_cvt_pk_bf16_f32 v68, v68, v69
	v_cvt_pk_bf16_f32 v69, v70, v71
	ds_write_b64 v117, v[68:69] offset:2048
	ds_bpermute_b32 v68, v170, v72
	s_waitcnt lgkmcnt(0)
	v_add_f32_e32 v112, v72, v68
	ds_bpermute_b32 v113, v171, v112
	s_and_saveexec_b64 s[6:7], vcc
	s_cbranch_execz .LBB0_141
	v_lshlrev_b64 v[68:69], 6, v[128:129]
	s_waitcnt lgkmcnt(0)
	v_add_f32_e32 v70, v112, v113
	v_lshl_add_u64 v[68:69], v[144:145], 0, v[68:69]
	global_store_dword v[68:69], v70, off sc1
.LBB0_141:
	s_or_b64 exec, exec, s[6:7]
	v_add_u32_e32 v112, 32, v132
	v_cmp_gt_i32_e64 s[6:7], s33, v112
	v_add_u32_e32 v68, 0xffffc020, v132
	s_waitcnt lgkmcnt(0)
	v_ashrrev_i32_e32 v113, 31, v112
	v_mov_b32_e32 v70, s71
	v_mov_b32_e32 v71, s55
	v_cndmask_b32_e64 v69, 0, v113, s[6:7]
	v_cndmask_b32_e64 v68, v68, v112, s[6:7]
	v_cndmask_b32_e64 v71, v70, v71, s[6:7]
	v_mov_b32_e32 v70, s70
	v_mov_b32_e32 v72, s54
	v_cndmask_b32_e64 v70, v70, v72, s[6:7]
	v_lshlrev_b64 v[68:69], 12, v[68:69]
	v_readlane_b32 s8, v254, 50
	v_lshl_add_u64 v[68:69], v[70:71], 0, v[68:69]
	v_lshlrev_b64 v[70:71], 12, v[112:113]
	v_readlane_b32 s9, v254, 51
	v_lshl_add_u64 v[114:115], v[68:69], 0, v[150:151]
	v_readlane_b32 s10, v254, 52
	v_lshl_add_u64 v[70:71], s[8:9], 0, v[70:71]
	v_cndmask_b32_e64 v69, v69, v71, s[4:5]
	v_cndmask_b32_e64 v68, v68, v70, s[4:5]
	v_lshl_add_u64 v[72:73], v[68:69], 0, v[150:151]
	s_barrier
	global_load_dwordx4 v[68:71], v[72:73], off
	global_load_dwordx4 v[232:235], v[72:73], off offset:64
	global_load_dwordx4 v[236:239], v[72:73], off offset:128
	global_load_dwordx4 v[240:243], v[72:73], off offset:192
	v_readlane_b32 s11, v254, 53
	v_readlane_b32 s12, v254, 54
	v_readlane_b32 s13, v254, 55
	v_readlane_b32 s14, v254, 56
	v_readlane_b32 s15, v254, 57
	v_readlane_b32 s16, v254, 58
	v_readlane_b32 s17, v254, 59
	v_readlane_b32 s18, v254, 60
	v_readlane_b32 s19, v254, 61
	v_readlane_b32 s20, v254, 62
	v_readlane_b32 s21, v254, 63
	v_readlane_b32 s22, v255, 0
	v_readlane_b32 s23, v255, 1
	s_waitcnt vmcnt(3)
	v_pk_fma_f32 v[68:69], v[108:109], v[28:29], v[68:69]
	s_nop 0
	v_mul_f32_e32 v74, v69, v69
	v_pk_fma_f32 v[70:71], v[110:111], v[30:31], v[70:71]
	v_fmac_f32_e32 v74, v68, v68
	v_fmac_f32_e32 v74, v70, v70
	global_store_dwordx4 v[114:115], v[68:71], off
	v_fmac_f32_e32 v74, v71, v71
	s_nop 0
	v_pk_mul_f32 v[70:71], v[160:161], v[70:71]
	v_pk_mul_f32 v[68:69], v[162:163], v[68:69]
	s_nop 0
	v_cvt_pk_bf16_f32 v68, v68, v69
	v_cvt_pk_bf16_f32 v69, v70, v71
	ds_write_b64 v124, v[68:69] offset:4096
	s_nop 1
	s_waitcnt vmcnt(3)
	v_pk_fma_f32 v[68:69], v[104:105], v[24:25], v[232:233]
	s_nop 0
	v_mul_f32_e32 v75, v69, v69
	v_pk_fma_f32 v[70:71], v[106:107], v[26:27], v[234:235]
	v_fmac_f32_e32 v75, v68, v68
	v_fmac_f32_e32 v75, v70, v70
	global_store_dwordx4 v[114:115], v[68:71], off offset:64
	v_fmac_f32_e32 v75, v71, v71
	v_add_f32_e32 v74, v74, v75
	v_pk_mul_f32 v[70:71], v[156:157], v[70:71]
	v_pk_mul_f32 v[68:69], v[158:159], v[68:69]
	s_nop 0
	v_cvt_pk_bf16_f32 v68, v68, v69
	v_cvt_pk_bf16_f32 v69, v70, v71
	ds_write_b64 v120, v[68:69] offset:4096
	s_nop 1
	s_waitcnt vmcnt(3)
; DI unsigned pk2(float a, float b) { f32x2 v = {a, b}; bf2_t r = __builtin_convertvector(v, bf2_t); return __builtin_bit_cast(unsigned, r); }
;     static DI void run(const f32x4 (&acc)[8][4], const TileCtx& tc, const Params& p, ldsp_t wb) {
;     ...
;             for (int mm = 0; mm < 4; ++mm) { __builtin_amdgcn_sched_barrier(0);
;                 const int m = h * 4 + mm;
;                 const int row = tc.brow + tc.wr * 128 + m * 16 + tc.fr;
;                 float* xr = xrow_ptr(p, row) + col0;
;                 const float* xs = (EK == 1 && tc.l == 0) ? p.x + (size_t)row * DM + col0 : xr;
;                 float part = 0.f;
; #pragma unroll
;                 for (int n = 0; n < 4; ++n) {
;                     f32x4 xv = *(const f32x4*)(xs + n * 16);
;                     xv += gv[n] * acc[m][n];
;                     *(f32x4*)(xr + n * 16) = xv;
;                     if (has_next) {
;                         part += xv[0] * xv[0] + xv[1] * xv[1] + xv[2] * xv[2] + xv[3] * xv[3];
;                         const f32x4 hv = xv * av[n];
;                         u32x2 w; w[0] = pk2(hv[0], hv[1]); w[1] = pk2(hv[2], hv[3]);
;                         wave_put(wb, mm * 16 + tc.fr, n, tc.fq, w);
;                     }
;                 }
;                 if (has_next) {
;                     part += __shfl_xor(part, 16);
;                     part += __shfl_xor(part, 32);
;                     if (tc.fq == 0) ssp[(size_t)row * 16] = part;
;                 }
;             }
;             if (has_next) wave_rows_store(wb, tc.lane, p.H + (size_t)(tc.brow + tc.wr * 128 + h * 64) * DM + tc.bcol + tc.wc * 64, DM);
	v_pk_fma_f32 v[68:69], v[100:101], v[20:21], v[236:237]
	s_nop 0
	v_mul_f32_e32 v75, v69, v69
	v_pk_fma_f32 v[70:71], v[102:103], v[22:23], v[238:239]
	v_fmac_f32_e32 v75, v68, v68
	v_fmac_f32_e32 v75, v70, v70
	global_store_dwordx4 v[114:115], v[68:71], off offset:128
	v_fmac_f32_e32 v75, v71, v71
	v_add_f32_e32 v74, v74, v75
	v_pk_mul_f32 v[70:71], v[152:153], v[70:71]
	v_pk_mul_f32 v[68:69], v[154:155], v[68:69]
	s_nop 0
	v_cvt_pk_bf16_f32 v68, v68, v69
	v_cvt_pk_bf16_f32 v69, v70, v71
	ds_write_b64 v116, v[68:69] offset:4096
	s_nop 1
	s_waitcnt vmcnt(3)
	v_pk_fma_f32 v[68:69], v[96:97], v[4:5], v[240:241]
	s_nop 0
	v_mul_f32_e32 v72, v69, v69
	v_pk_fma_f32 v[70:71], v[98:99], v[6:7], v[242:243]
	v_fmac_f32_e32 v72, v68, v68
	v_fmac_f32_e32 v72, v70, v70
	global_store_dwordx4 v[114:115], v[68:71], off offset:192
	v_fmac_f32_e32 v72, v71, v71
	v_add_f32_e32 v72, v74, v72
	v_pk_mul_f32 v[70:71], v[146:147], v[70:71]
	v_pk_mul_f32 v[68:69], v[148:149], v[68:69]
	s_nop 0
	v_cvt_pk_bf16_f32 v68, v68, v69
	v_cvt_pk_bf16_f32 v69, v70, v71
	ds_write_b64 v117, v[68:69] offset:4096
	ds_bpermute_b32 v68, v170, v72
	s_waitcnt lgkmcnt(0)
	v_add_f32_e32 v96, v72, v68
	ds_bpermute_b32 v97, v171, v96
	s_and_saveexec_b64 s[6:7], vcc
	s_cbranch_execz .LBB0_143
	v_lshlrev_b64 v[68:69], 6, v[112:113]
	s_waitcnt lgkmcnt(0)
	v_add_f32_e32 v70, v96, v97
	v_lshl_add_u64 v[68:69], v[144:145], 0, v[68:69]
	global_store_dword v[68:69], v70, off sc1
.LBB0_143:
	s_or_b64 exec, exec, s[6:7]
	v_add_u32_e32 v96, 48, v132
	v_cmp_gt_i32_e64 s[6:7], s33, v96
	v_add_u32_e32 v68, 0xffffc030, v132
	s_waitcnt lgkmcnt(0)
	v_ashrrev_i32_e32 v97, 31, v96
	v_mov_b32_e32 v70, s71
	v_mov_b32_e32 v71, s55
	v_cndmask_b32_e64 v69, 0, v97, s[6:7]
	v_cndmask_b32_e64 v68, v68, v96, s[6:7]
	v_cndmask_b32_e64 v71, v70, v71, s[6:7]
	v_mov_b32_e32 v70, s70
	v_mov_b32_e32 v72, s54
	v_cndmask_b32_e64 v70, v70, v72, s[6:7]
	v_lshlrev_b64 v[68:69], 12, v[68:69]
	v_readlane_b32 s8, v254, 50
	v_lshl_add_u64 v[68:69], v[70:71], 0, v[68:69]
	v_lshlrev_b64 v[70:71], 12, v[96:97]
	v_readlane_b32 s9, v254, 51
	v_lshl_add_u64 v[98:99], v[68:69], 0, v[150:151]
	v_readlane_b32 s10, v254, 52
	v_lshl_add_u64 v[70:71], s[8:9], 0, v[70:71]
	v_cndmask_b32_e64 v69, v69, v71, s[4:5]
	v_cndmask_b32_e64 v68, v68, v70, s[4:5]
	v_lshl_add_u64 v[72:73], v[68:69], 0, v[150:151]
	s_barrier
	global_load_dwordx4 v[68:71], v[72:73], off
	global_load_dwordx4 v[232:235], v[72:73], off offset:64
	global_load_dwordx4 v[236:239], v[72:73], off offset:128
	global_load_dwordx4 v[240:243], v[72:73], off offset:192
	v_readlane_b32 s11, v254, 53
	v_readlane_b32 s12, v254, 54
	v_readlane_b32 s13, v254, 55
	v_readlane_b32 s14, v254, 56
	v_readlane_b32 s15, v254, 57
	v_readlane_b32 s16, v254, 58
	v_readlane_b32 s17, v254, 59
	v_readlane_b32 s18, v254, 60
	v_readlane_b32 s19, v254, 61
	v_readlane_b32 s20, v254, 62
	v_readlane_b32 s21, v254, 63
	v_readlane_b32 s22, v255, 0
	v_readlane_b32 s23, v255, 1
	s_waitcnt vmcnt(3)
	v_pk_fma_f32 v[68:69], v[92:93], v[28:29], v[68:69]
	s_nop 0
	v_mul_f32_e32 v74, v69, v69
	v_pk_fma_f32 v[70:71], v[94:95], v[30:31], v[70:71]
	v_fmac_f32_e32 v74, v68, v68
	v_fmac_f32_e32 v74, v70, v70
	global_store_dwordx4 v[98:99], v[68:71], off
	v_fmac_f32_e32 v74, v71, v71
	s_nop 0
	v_pk_mul_f32 v[70:71], v[160:161], v[70:71]
	v_pk_mul_f32 v[68:69], v[162:163], v[68:69]
	s_nop 0
	v_cvt_pk_bf16_f32 v68, v68, v69
	v_cvt_pk_bf16_f32 v69, v70, v71
	ds_write_b64 v124, v[68:69] offset:6144
	s_nop 1
	s_waitcnt vmcnt(3)
	v_pk_fma_f32 v[68:69], v[88:89], v[24:25], v[232:233]
	s_nop 0
	v_mul_f32_e32 v75, v69, v69
	v_pk_fma_f32 v[70:71], v[90:91], v[26:27], v[234:235]
	v_fmac_f32_e32 v75, v68, v68
	v_fmac_f32_e32 v75, v70, v70
	global_store_dwordx4 v[98:99], v[68:71], off offset:64
	v_fmac_f32_e32 v75, v71, v71
	v_add_f32_e32 v74, v74, v75
	v_pk_mul_f32 v[70:71], v[156:157], v[70:71]
	v_pk_mul_f32 v[68:69], v[158:159], v[68:69]
	s_nop 0
	v_cvt_pk_bf16_f32 v68, v68, v69
	v_cvt_pk_bf16_f32 v69, v70, v71
	ds_write_b64 v120, v[68:69] offset:6144
	s_nop 1
	s_waitcnt vmcnt(3)
	v_pk_fma_f32 v[68:69], v[84:85], v[20:21], v[236:237]
	s_nop 0
	v_mul_f32_e32 v75, v69, v69
	v_pk_fma_f32 v[70:71], v[86:87], v[22:23], v[238:239]
	v_fmac_f32_e32 v75, v68, v68
	v_fmac_f32_e32 v75, v70, v70
	global_store_dwordx4 v[98:99], v[68:71], off offset:128
	v_fmac_f32_e32 v75, v71, v71
	v_add_f32_e32 v74, v74, v75
	v_pk_mul_f32 v[70:71], v[152:153], v[70:71]
	v_pk_mul_f32 v[68:69], v[154:155], v[68:69]
	s_nop 0
	v_cvt_pk_bf16_f32 v68, v68, v69
	v_cvt_pk_bf16_f32 v69, v70, v71
	ds_write_b64 v116, v[68:69] offset:6144
	s_nop 1
	s_waitcnt vmcnt(3)
	v_pk_fma_f32 v[68:69], v[80:81], v[4:5], v[240:241]
	s_nop 0
	v_mul_f32_e32 v72, v69, v69
	v_pk_fma_f32 v[70:71], v[82:83], v[6:7], v[242:243]
	v_fmac_f32_e32 v72, v68, v68
	v_fmac_f32_e32 v72, v70, v70
	global_store_dwordx4 v[98:99], v[68:71], off offset:192
	v_fmac_f32_e32 v72, v71, v71
	v_add_f32_e32 v72, v74, v72
	v_pk_mul_f32 v[70:71], v[146:147], v[70:71]
	v_pk_mul_f32 v[68:69], v[148:149], v[68:69]
	s_nop 0
	v_cvt_pk_bf16_f32 v68, v68, v69
	v_cvt_pk_bf16_f32 v69, v70, v71
	ds_write_b64 v117, v[68:69] offset:6144
	ds_bpermute_b32 v68, v170, v72
	s_waitcnt lgkmcnt(0)
	v_add_f32_e32 v80, v72, v68
	ds_bpermute_b32 v81, v171, v80
	s_and_saveexec_b64 s[6:7], vcc
	s_cbranch_execz .LBB0_145
	v_lshlrev_b64 v[68:69], 6, v[96:97]
	s_waitcnt lgkmcnt(0)
	v_add_f32_e32 v70, v80, v81
	v_lshl_add_u64 v[68:69], v[144:145], 0, v[68:69]
	global_store_dword v[68:69], v70, off sc1
; #define LDSP __attribute__((address_space(3)))
; DI unsigned pk2(float a, float b) { f32x2 v = {a, b}; bf2_t r = __builtin_convertvector(v, bf2_t); return __builtin_bit_cast(unsigned, r); }
; DI void wave_rows_store(ldsp_t wb, int lane, bf16_t* dst0, size_t ld) {
;     ...
;     for (int i = 0; i < 8; ++i) {
;         const int row = i * 8 + (lane >> 3), ch = lane & 7;
;         const u32x4 v = *(const LDSP u32x4*)(wb + row * 128 + ((ch ^ (row & 7)) << 4));
;         *(u32x4*)(dst0 + (size_t)row * ld + ch * 8) = v;
;     static DI void run(const f32x4 (&acc)[8][4], const TileCtx& tc, const Params& p, ldsp_t wb) {
;     ...
;             for (int mm = 0; mm < 4; ++mm) { __builtin_amdgcn_sched_barrier(0);
;                 const int m = h * 4 + mm;
;                 const int row = tc.brow + tc.wr * 128 + m * 16 + tc.fr;
;                 float* xr = xrow_ptr(p, row) + col0;
;                 const float* xs = (EK == 1 && tc.l == 0) ? p.x + (size_t)row * DM + col0 : xr;
;                 float part = 0.f;
; #pragma unroll
;                 for (int n = 0; n < 4; ++n) {
;                     f32x4 xv = *(const f32x4*)(xs + n * 16);
;                     xv += gv[n] * acc[m][n];
;                     *(f32x4*)(xr + n * 16) = xv;
;                     if (has_next) {
;                         part += xv[0] * xv[0] + xv[1] * xv[1] + xv[2] * xv[2] + xv[3] * xv[3];
;                         const f32x4 hv = xv * av[n];
;                         u32x2 w; w[0] = pk2(hv[0], hv[1]); w[1] = pk2(hv[2], hv[3]);
;                         wave_put(wb, mm * 16 + tc.fr, n, tc.fq, w);
;                     }
;                 }
;                 if (has_next) {
;                     part += __shfl_xor(part, 16);
;                     part += __shfl_xor(part, 32);
;                     if (tc.fq == 0) ssp[(size_t)row * 16] = part;
;                 }
;             }
;             if (has_next) wave_rows_store(wb, tc.lane, p.H + (size_t)(tc.brow + tc.wr * 128 + h * 64) * DM + tc.bcol + tc.wc * 64, DM);
.LBB0_145:
	s_or_b64 exec, exec, s[6:7]
	v_lshrrev_b32_e32 v80, 3, v175
	v_xor_b32_e32 v70, v80, v175
	v_ashrrev_i32_e32 v165, 31, v164
	v_lshlrev_b32_e32 v70, 4, v70
	v_lshlrev_b64 v[68:69], 11, v[164:165]
	v_and_b32_e32 v70, 0x70, v70
	v_lshl_add_u64 v[68:69], s[82:83], 0, v[68:69]
	s_ashr_i32 s39, s38, 31
	s_waitcnt lgkmcnt(0)
	v_add_u32_e32 v81, v176, v70
	v_lshlrev_b32_e32 v70, 3, v175
	v_lshl_add_u64 v[68:69], s[38:39], 1, v[68:69]
	v_lshlrev_b32_e32 v88, 1, v172
	v_mov_b32_e32 v89, v193
	v_and_b32_e32 v70, 56, v70
	v_lshl_add_u64 v[68:69], v[68:69], 0, v[88:89]
	v_lshlrev_b32_e32 v96, 1, v70
	v_mov_b32_e32 v97, v193
	v_lshl_add_u64 v[72:73], v[68:69], 0, v[96:97]
	v_lshlrev_b32_e32 v68, 7, v80
	v_add_u32_e32 v111, v81, v68
	ds_read_b128 v[68:71], v111
	v_lshlrev_b32_e32 v192, 11, v80
	v_lshl_add_u64 v[74:75], v[72:73], 0, v[192:193]
	v_mov_b32_e32 v95, v193
	v_mov_b32_e32 v93, v193
	s_waitcnt lgkmcnt(0)
	global_store_dwordx4 v[74:75], v[68:71], off sc1
	v_or_b32_e32 v74, 8, v80
	v_lshlrev_b32_e32 v94, 11, v74
	v_lshlrev_b32_e32 v68, 7, v74
	v_add_u32_e32 v110, v81, v68
	ds_read_b128 v[68:71], v110
	v_lshl_add_u64 v[74:75], v[72:73], 0, v[94:95]
	v_mov_b32_e32 v91, v193
	v_mov_b32_e32 v83, v193
	v_mov_b32_e32 v87, v193
	s_waitcnt lgkmcnt(0)
	global_store_dwordx4 v[74:75], v[68:71], off sc1
	v_or_b32_e32 v74, 16, v80
	v_lshlrev_b32_e32 v92, 11, v74
	v_lshlrev_b32_e32 v68, 7, v74
	v_add_u32_e32 v109, v81, v68
	ds_read_b128 v[68:71], v109
	v_lshl_add_u64 v[74:75], v[72:73], 0, v[92:93]
	v_mov_b32_e32 v85, v193
	s_waitcnt lgkmcnt(0)
	global_store_dwordx4 v[74:75], v[68:71], off sc1
	v_or_b32_e32 v74, 24, v80
	s_nop 0
	v_lshlrev_b32_e32 v68, 7, v74
	v_add_u32_e32 v108, v81, v68
	ds_read_b128 v[68:71], v108
	v_lshlrev_b32_e32 v90, 11, v74
	v_lshl_add_u64 v[74:75], v[72:73], 0, v[90:91]
	s_waitcnt lgkmcnt(0)
	global_store_dwordx4 v[74:75], v[68:71], off sc1
	v_or_b32_e32 v74, 32, v80
	s_nop 0
	v_lshlrev_b32_e32 v68, 7, v74
	v_add_u32_e32 v104, v81, v68
	ds_read_b128 v[68:71], v104
	v_lshlrev_b32_e32 v82, 11, v74
	v_lshl_add_u64 v[74:75], v[72:73], 0, v[82:83]
	s_waitcnt lgkmcnt(0)
	global_store_dwordx4 v[74:75], v[68:71], off sc1
	v_or_b32_e32 v74, 40, v80
	s_nop 0
	v_lshlrev_b32_e32 v68, 7, v74
	v_add_u32_e32 v105, v81, v68
	ds_read_b128 v[68:71], v105
	v_lshlrev_b32_e32 v86, 11, v74
	v_lshl_add_u64 v[74:75], v[72:73], 0, v[86:87]
	s_waitcnt lgkmcnt(0)
	global_store_dwordx4 v[74:75], v[68:71], off sc1
	v_or_b32_e32 v74, 48, v80
	s_nop 0
	v_lshlrev_b32_e32 v68, 7, v74
	v_add_u32_e32 v106, v81, v68
	ds_read_b128 v[68:71], v106
	v_lshlrev_b32_e32 v84, 11, v74
	v_lshl_add_u64 v[74:75], v[72:73], 0, v[84:85]
	s_waitcnt lgkmcnt(0)
	global_store_dwordx4 v[74:75], v[68:71], off sc1
	v_or_b32_e32 v74, 56, v80
	s_nop 0
	v_lshlrev_b32_e32 v68, 7, v74
	v_add_u32_e32 v107, v81, v68
	ds_read_b128 v[68:71], v107
	v_lshlrev_b32_e32 v80, 11, v74
	v_mov_b32_e32 v81, v193
	v_lshl_add_u64 v[72:73], v[72:73], 0, v[80:81]
	s_waitcnt lgkmcnt(0)
	global_store_dwordx4 v[72:73], v[68:71], off sc1
	v_add3_u32 v98, v174, s41, 64
	v_or_b32_e32 v100, v98, v173
	v_cmp_gt_i32_e64 s[6:7], s33, v100
	v_add_u32_e32 v68, 0xffffc000, v100
	v_ashrrev_i32_e32 v101, 31, v100
	v_mov_b32_e32 v70, s71
	v_mov_b32_e32 v71, s55
	v_cndmask_b32_e64 v69, 0, v101, s[6:7]
	v_cndmask_b32_e64 v68, v68, v100, s[6:7]
	v_cndmask_b32_e64 v71, v70, v71, s[6:7]
	v_mov_b32_e32 v70, s70
	v_mov_b32_e32 v72, s54
	v_cndmask_b32_e64 v70, v70, v72, s[6:7]
	v_lshlrev_b64 v[68:69], 12, v[68:69]
	v_readlane_b32 s8, v254, 50
	v_lshl_add_u64 v[68:69], v[70:71], 0, v[68:69]
	v_lshlrev_b64 v[70:71], 12, v[100:101]
	v_readlane_b32 s9, v254, 51
	v_lshl_add_u64 v[102:103], v[68:69], 0, v[150:151]
	v_readlane_b32 s10, v254, 52
	v_lshl_add_u64 v[70:71], s[8:9], 0, v[70:71]
	v_cndmask_b32_e64 v69, v69, v71, s[4:5]
	v_cndmask_b32_e64 v68, v68, v70, s[4:5]
	v_lshl_add_u64 v[72:73], v[68:69], 0, v[150:151]
	s_barrier
	global_load_dwordx4 v[68:71], v[72:73], off
	global_load_dwordx4 v[232:235], v[72:73], off offset:64
	global_load_dwordx4 v[236:239], v[72:73], off offset:128
	global_load_dwordx4 v[240:243], v[72:73], off offset:192
	v_readlane_b32 s11, v254, 53
	v_readlane_b32 s12, v254, 54
	v_readlane_b32 s13, v254, 55
	v_readlane_b32 s14, v254, 56
	v_readlane_b32 s15, v254, 57
	v_readlane_b32 s16, v254, 58
	v_readlane_b32 s17, v254, 59
	v_readlane_b32 s18, v254, 60
	v_readlane_b32 s19, v254, 61
	v_readlane_b32 s20, v254, 62
	v_readlane_b32 s21, v254, 63
	v_readlane_b32 s22, v255, 0
	v_readlane_b32 s23, v255, 1
	s_waitcnt vmcnt(3)
	v_pk_fma_f32 v[68:69], v[76:77], v[28:29], v[68:69]
	s_nop 0
	v_mul_f32_e32 v74, v69, v69
	v_pk_fma_f32 v[70:71], v[78:79], v[30:31], v[70:71]
	v_fmac_f32_e32 v74, v68, v68
	v_fmac_f32_e32 v74, v70, v70
	global_store_dwordx4 v[102:103], v[68:71], off
	v_fmac_f32_e32 v74, v71, v71
	s_nop 0
	v_pk_mul_f32 v[70:71], v[160:161], v[70:71]
	v_pk_mul_f32 v[68:69], v[162:163], v[68:69]
	s_nop 0
	v_cvt_pk_bf16_f32 v68, v68, v69
	v_cvt_pk_bf16_f32 v69, v70, v71
	ds_write_b64 v124, v[68:69]
	s_nop 1
	s_waitcnt vmcnt(3)
	v_pk_fma_f32 v[68:69], v[198:199], v[24:25], v[232:233]
	s_nop 0
	v_mul_f32_e32 v75, v69, v69
	v_pk_fma_f32 v[70:71], v[200:201], v[26:27], v[234:235]
	v_fmac_f32_e32 v75, v68, v68
	v_fmac_f32_e32 v75, v70, v70
	global_store_dwordx4 v[102:103], v[68:71], off offset:64
	v_fmac_f32_e32 v75, v71, v71
	v_add_f32_e32 v74, v74, v75
	v_pk_mul_f32 v[70:71], v[156:157], v[70:71]
	v_pk_mul_f32 v[68:69], v[158:159], v[68:69]
	s_nop 0
	v_cvt_pk_bf16_f32 v68, v68, v69
	v_cvt_pk_bf16_f32 v69, v70, v71
	ds_write_b64 v120, v[68:69]
	s_nop 1
	s_waitcnt vmcnt(3)
	v_pk_fma_f32 v[68:69], v[194:195], v[20:21], v[236:237]
	s_nop 0
	v_mul_f32_e32 v75, v69, v69
	v_pk_fma_f32 v[70:71], v[196:197], v[22:23], v[238:239]
	v_fmac_f32_e32 v75, v68, v68
	v_fmac_f32_e32 v75, v70, v70
	global_store_dwordx4 v[102:103], v[68:71], off offset:128
	v_fmac_f32_e32 v75, v71, v71
	v_add_f32_e32 v74, v74, v75
	v_pk_mul_f32 v[70:71], v[152:153], v[70:71]
	v_pk_mul_f32 v[68:69], v[154:155], v[68:69]
	s_nop 0
	v_cvt_pk_bf16_f32 v68, v68, v69
	v_cvt_pk_bf16_f32 v69, v70, v71
	ds_write_b64 v116, v[68:69]
	s_nop 1
	s_waitcnt vmcnt(3)
	v_pk_fma_f32 v[64:65], v[64:65], v[4:5], v[240:241]
	s_nop 0
	v_mul_f32_e32 v68, v65, v65
	v_pk_fma_f32 v[66:67], v[66:67], v[6:7], v[242:243]
	v_fmac_f32_e32 v68, v64, v64
	v_fmac_f32_e32 v68, v66, v66
	global_store_dwordx4 v[102:103], v[64:67], off offset:192
	v_fmac_f32_e32 v68, v67, v67
	v_add_f32_e32 v68, v74, v68
	v_pk_mul_f32 v[66:67], v[146:147], v[66:67]
	v_pk_mul_f32 v[64:65], v[148:149], v[64:65]
	s_nop 0
	v_cvt_pk_bf16_f32 v64, v64, v65
	v_cvt_pk_bf16_f32 v65, v66, v67
	ds_write_b64 v117, v[64:65]
	ds_bpermute_b32 v64, v170, v68
	s_waitcnt lgkmcnt(0)
	v_add_f32_e32 v64, v68, v64
	ds_bpermute_b32 v65, v171, v64
	s_and_saveexec_b64 s[6:7], vcc
	s_cbranch_execz .LBB0_147
	s_waitcnt lgkmcnt(0)
	v_add_f32_e32 v66, v64, v65
	v_lshlrev_b64 v[64:65], 6, v[100:101]
	v_lshl_add_u64 v[64:65], v[144:145], 0, v[64:65]
	global_store_dword v[64:65], v66, off sc1
; DI unsigned pk2(float a, float b) { f32x2 v = {a, b}; bf2_t r = __builtin_convertvector(v, bf2_t); return __builtin_bit_cast(unsigned, r); }
;     static DI void run(const f32x4 (&acc)[8][4], const TileCtx& tc, const Params& p, ldsp_t wb) {
;     ...
;             for (int mm = 0; mm < 4; ++mm) { __builtin_amdgcn_sched_barrier(0);
;                 const int m = h * 4 + mm;
;                 const int row = tc.brow + tc.wr * 128 + m * 16 + tc.fr;
;                 float* xr = xrow_ptr(p, row) + col0;
;                 const float* xs = (EK == 1 && tc.l == 0) ? p.x + (size_t)row * DM + col0 : xr;
;                 float part = 0.f;
; #pragma unroll
;                 for (int n = 0; n < 4; ++n) {
;                     f32x4 xv = *(const f32x4*)(xs + n * 16);
;                     xv += gv[n] * acc[m][n];
;                     *(f32x4*)(xr + n * 16) = xv;
;                     if (has_next) {
;                         part += xv[0] * xv[0] + xv[1] * xv[1] + xv[2] * xv[2] + xv[3] * xv[3];
;                         const f32x4 hv = xv * av[n];
;                         u32x2 w; w[0] = pk2(hv[0], hv[1]); w[1] = pk2(hv[2], hv[3]);
;                         wave_put(wb, mm * 16 + tc.fr, n, tc.fq, w);
;                     }
;                 }
;                 if (has_next) {
;                     part += __shfl_xor(part, 16);
;                     part += __shfl_xor(part, 32);
;                     if (tc.fq == 0) ssp[(size_t)row * 16] = part;
;                 }
.LBB0_147:
	s_or_b64 exec, exec, s[6:7]
	v_add_u32_e32 v64, 0x50, v132
	v_cmp_gt_i32_e64 s[6:7], s33, v64
	v_add_u32_e32 v66, 0xffffc050, v132
	s_waitcnt lgkmcnt(0)
	v_ashrrev_i32_e32 v65, 31, v64
	v_mov_b32_e32 v68, s71
	v_mov_b32_e32 v69, s55
	v_cndmask_b32_e64 v67, 0, v65, s[6:7]
	v_cndmask_b32_e64 v66, v66, v64, s[6:7]
	v_cndmask_b32_e64 v69, v68, v69, s[6:7]
	v_mov_b32_e32 v68, s70
	v_mov_b32_e32 v70, s54
	v_readlane_b32 s8, v254, 50
	v_cndmask_b32_e64 v68, v68, v70, s[6:7]
	v_lshlrev_b64 v[66:67], 12, v[66:67]
	v_lshlrev_b64 v[70:71], 12, v[64:65]
	v_readlane_b32 s9, v254, 51
	v_lshl_add_u64 v[68:69], v[68:69], 0, v[66:67]
	v_lshl_add_u64 v[66:67], v[68:69], 0, v[150:151]
	v_lshl_add_u64 v[70:71], s[8:9], 0, v[70:71]
	v_cndmask_b32_e64 v69, v69, v71, s[4:5]
	v_cndmask_b32_e64 v68, v68, v70, s[4:5]
	v_lshl_add_u64 v[72:73], v[68:69], 0, v[150:151]
	s_barrier
	global_load_dwordx4 v[68:71], v[72:73], off
	global_load_dwordx4 v[232:235], v[72:73], off offset:64
	global_load_dwordx4 v[236:239], v[72:73], off offset:128
	global_load_dwordx4 v[240:243], v[72:73], off offset:192
	v_readlane_b32 s10, v254, 52
	v_readlane_b32 s11, v254, 53
	v_readlane_b32 s12, v254, 54
	v_readlane_b32 s13, v254, 55
	v_readlane_b32 s14, v254, 56
	v_readlane_b32 s15, v254, 57
	v_readlane_b32 s16, v254, 58
	v_readlane_b32 s17, v254, 59
	v_readlane_b32 s18, v254, 60
	v_readlane_b32 s19, v254, 61
	v_readlane_b32 s20, v254, 62
	v_readlane_b32 s21, v254, 63
	v_readlane_b32 s22, v255, 0
	v_readlane_b32 s23, v255, 1
	s_waitcnt vmcnt(3)
	v_pk_fma_f32 v[60:61], v[60:61], v[28:29], v[68:69]
	s_nop 0
	v_mul_f32_e32 v68, v61, v61
	v_pk_fma_f32 v[62:63], v[62:63], v[30:31], v[70:71]
	v_fmac_f32_e32 v68, v60, v60
	v_fmac_f32_e32 v68, v62, v62
	global_store_dwordx4 v[66:67], v[60:63], off
	v_fmac_f32_e32 v68, v63, v63
	s_nop 0
	v_pk_mul_f32 v[62:63], v[160:161], v[62:63]
	v_pk_mul_f32 v[60:61], v[162:163], v[60:61]
	s_nop 0
	v_cvt_pk_bf16_f32 v60, v60, v61
	v_cvt_pk_bf16_f32 v61, v62, v63
	ds_write_b64 v124, v[60:61] offset:2048
	s_nop 1
	s_waitcnt vmcnt(3)
	v_pk_fma_f32 v[56:57], v[56:57], v[24:25], v[232:233]
	s_nop 0
	v_mul_f32_e32 v60, v57, v57
	v_pk_fma_f32 v[58:59], v[58:59], v[26:27], v[234:235]
	v_fmac_f32_e32 v60, v56, v56
	v_fmac_f32_e32 v60, v58, v58
	global_store_dwordx4 v[66:67], v[56:59], off offset:64
	v_fmac_f32_e32 v60, v59, v59
	v_add_f32_e32 v60, v68, v60
	v_pk_mul_f32 v[58:59], v[156:157], v[58:59]
	v_pk_mul_f32 v[56:57], v[158:159], v[56:57]
	s_nop 0
	v_cvt_pk_bf16_f32 v56, v56, v57
	v_cvt_pk_bf16_f32 v57, v58, v59
	ds_write_b64 v120, v[56:57] offset:2048
	s_nop 1
	s_waitcnt vmcnt(3)
	v_pk_fma_f32 v[52:53], v[52:53], v[20:21], v[236:237]
	s_nop 0
	v_mul_f32_e32 v56, v53, v53
	v_pk_fma_f32 v[54:55], v[54:55], v[22:23], v[238:239]
	v_fmac_f32_e32 v56, v52, v52
	v_fmac_f32_e32 v56, v54, v54
	global_store_dwordx4 v[66:67], v[52:55], off offset:128
	v_fmac_f32_e32 v56, v55, v55
	v_add_f32_e32 v56, v60, v56
	v_pk_mul_f32 v[54:55], v[152:153], v[54:55]
	v_pk_mul_f32 v[52:53], v[154:155], v[52:53]
	s_nop 0
	v_cvt_pk_bf16_f32 v52, v52, v53
	v_cvt_pk_bf16_f32 v53, v54, v55
	ds_write_b64 v116, v[52:53] offset:2048
	s_nop 1
	s_waitcnt vmcnt(3)
	v_pk_fma_f32 v[48:49], v[48:49], v[4:5], v[240:241]
	s_nop 0
	v_mul_f32_e32 v52, v49, v49
	v_pk_fma_f32 v[50:51], v[50:51], v[6:7], v[242:243]
	v_fmac_f32_e32 v52, v48, v48
	v_fmac_f32_e32 v52, v50, v50
	global_store_dwordx4 v[66:67], v[48:51], off offset:192
	v_fmac_f32_e32 v52, v51, v51
	v_add_f32_e32 v52, v56, v52
	v_pk_mul_f32 v[50:51], v[146:147], v[50:51]
	v_pk_mul_f32 v[48:49], v[148:149], v[48:49]
	s_nop 0
	v_cvt_pk_bf16_f32 v48, v48, v49
	v_cvt_pk_bf16_f32 v49, v50, v51
	ds_write_b64 v117, v[48:49] offset:2048
	ds_bpermute_b32 v48, v170, v52
	s_waitcnt lgkmcnt(0)
	v_add_f32_e32 v48, v52, v48
	ds_bpermute_b32 v49, v171, v48
	s_and_saveexec_b64 s[6:7], vcc
	s_cbranch_execz .LBB0_149
	s_waitcnt lgkmcnt(0)
	v_add_f32_e32 v50, v48, v49
	v_lshlrev_b64 v[48:49], 6, v[64:65]
	v_lshl_add_u64 v[48:49], v[144:145], 0, v[48:49]
	global_store_dword v[48:49], v50, off sc1
.LBB0_149:
	s_or_b64 exec, exec, s[6:7]
	v_add_u32_e32 v48, 0x60, v132
	v_cmp_gt_i32_e64 s[6:7], s33, v48
	v_add_u32_e32 v50, 0xffffc060, v132
	s_waitcnt lgkmcnt(0)
	v_ashrrev_i32_e32 v49, 31, v48
	v_mov_b32_e32 v52, s71
	v_mov_b32_e32 v53, s55
	v_cndmask_b32_e64 v51, 0, v49, s[6:7]
	v_cndmask_b32_e64 v50, v50, v48, s[6:7]
	v_cndmask_b32_e64 v53, v52, v53, s[6:7]
	v_mov_b32_e32 v52, s70
	v_mov_b32_e32 v54, s54
	v_readlane_b32 s8, v254, 50
	v_cndmask_b32_e64 v52, v52, v54, s[6:7]
	v_lshlrev_b64 v[50:51], 12, v[50:51]
	v_lshlrev_b64 v[54:55], 12, v[48:49]
	v_readlane_b32 s9, v254, 51
	v_lshl_add_u64 v[52:53], v[52:53], 0, v[50:51]
	v_lshl_add_u64 v[50:51], v[52:53], 0, v[150:151]
	v_lshl_add_u64 v[54:55], s[8:9], 0, v[54:55]
	v_cndmask_b32_e64 v53, v53, v55, s[4:5]
	v_cndmask_b32_e64 v52, v52, v54, s[4:5]
	v_lshl_add_u64 v[56:57], v[52:53], 0, v[150:151]
	s_barrier
; DI unsigned pk2(float a, float b) { f32x2 v = {a, b}; bf2_t r = __builtin_convertvector(v, bf2_t); return __builtin_bit_cast(unsigned, r); }
;     static DI void run(const f32x4 (&acc)[8][4], const TileCtx& tc, const Params& p, ldsp_t wb) {
;     ...
;                 const int row = tc.brow + tc.wr * 128 + m * 16 + tc.fr;
;                 float* xr = xrow_ptr(p, row) + col0;
;                 const float* xs = (EK == 1 && tc.l == 0) ? p.x + (size_t)row * DM + col0 : xr;
;                 float part = 0.f;
; #pragma unroll
;                 for (int n = 0; n < 4; ++n) {
;                     f32x4 xv = *(const f32x4*)(xs + n * 16);
;                     xv += gv[n] * acc[m][n];
;                     *(f32x4*)(xr + n * 16) = xv;
;                     if (has_next) {
;                         part += xv[0] * xv[0] + xv[1] * xv[1] + xv[2] * xv[2] + xv[3] * xv[3];
;                         const f32x4 hv = xv * av[n];
;                         u32x2 w; w[0] = pk2(hv[0], hv[1]); w[1] = pk2(hv[2], hv[3]);
;                         wave_put(wb, mm * 16 + tc.fr, n, tc.fq, w);
;                     }
;                 }
;                 if (has_next) {
;                     part += __shfl_xor(part, 16);
;                     part += __shfl_xor(part, 32);
;                     if (tc.fq == 0) ssp[(size_t)row * 16] = part;
;                 }
	global_load_dwordx4 v[52:55], v[56:57], off
	global_load_dwordx4 v[232:235], v[56:57], off offset:64
	global_load_dwordx4 v[236:239], v[56:57], off offset:128
	global_load_dwordx4 v[240:243], v[56:57], off offset:192
	v_readlane_b32 s10, v254, 52
	v_readlane_b32 s11, v254, 53
	v_readlane_b32 s12, v254, 54
	v_readlane_b32 s13, v254, 55
	v_readlane_b32 s14, v254, 56
	v_readlane_b32 s15, v254, 57
	v_readlane_b32 s16, v254, 58
	v_readlane_b32 s17, v254, 59
	v_readlane_b32 s18, v254, 60
	v_readlane_b32 s19, v254, 61
	v_readlane_b32 s20, v254, 62
	v_readlane_b32 s21, v254, 63
	v_readlane_b32 s22, v255, 0
	v_readlane_b32 s23, v255, 1
	s_waitcnt vmcnt(3)
	v_pk_fma_f32 v[44:45], v[44:45], v[28:29], v[52:53]
	s_nop 0
	v_mul_f32_e32 v52, v45, v45
	v_pk_fma_f32 v[46:47], v[46:47], v[30:31], v[54:55]
	v_fmac_f32_e32 v52, v44, v44
	v_fmac_f32_e32 v52, v46, v46
	global_store_dwordx4 v[50:51], v[44:47], off
	v_fmac_f32_e32 v52, v47, v47
	s_nop 0
	v_pk_mul_f32 v[46:47], v[160:161], v[46:47]
	v_pk_mul_f32 v[44:45], v[162:163], v[44:45]
	s_nop 0
	v_cvt_pk_bf16_f32 v44, v44, v45
	v_cvt_pk_bf16_f32 v45, v46, v47
	ds_write_b64 v124, v[44:45] offset:4096
	s_nop 1
	s_waitcnt vmcnt(3)
	v_pk_fma_f32 v[40:41], v[40:41], v[24:25], v[232:233]
	s_nop 0
	v_mul_f32_e32 v44, v41, v41
	v_pk_fma_f32 v[42:43], v[42:43], v[26:27], v[234:235]
	v_fmac_f32_e32 v44, v40, v40
	v_fmac_f32_e32 v44, v42, v42
	global_store_dwordx4 v[50:51], v[40:43], off offset:64
	v_fmac_f32_e32 v44, v43, v43
	v_add_f32_e32 v44, v52, v44
	v_pk_mul_f32 v[42:43], v[156:157], v[42:43]
	v_pk_mul_f32 v[40:41], v[158:159], v[40:41]
	s_nop 0
	v_cvt_pk_bf16_f32 v40, v40, v41
	v_cvt_pk_bf16_f32 v41, v42, v43
	ds_write_b64 v120, v[40:41] offset:4096
	s_nop 1
	s_waitcnt vmcnt(3)
	v_pk_fma_f32 v[36:37], v[36:37], v[20:21], v[236:237]
	s_nop 0
	v_mul_f32_e32 v40, v37, v37
	v_pk_fma_f32 v[38:39], v[38:39], v[22:23], v[238:239]
	v_fmac_f32_e32 v40, v36, v36
	v_fmac_f32_e32 v40, v38, v38
	global_store_dwordx4 v[50:51], v[36:39], off offset:128
	v_fmac_f32_e32 v40, v39, v39
	v_add_f32_e32 v40, v44, v40
	v_pk_mul_f32 v[38:39], v[152:153], v[38:39]
	v_pk_mul_f32 v[36:37], v[154:155], v[36:37]
	s_nop 0
	v_cvt_pk_bf16_f32 v36, v36, v37
	v_cvt_pk_bf16_f32 v37, v38, v39
	ds_write_b64 v116, v[36:37] offset:4096
	s_nop 1
	s_waitcnt vmcnt(3)
	v_pk_fma_f32 v[32:33], v[32:33], v[4:5], v[240:241]
	s_nop 0
	v_mul_f32_e32 v36, v33, v33
	v_pk_fma_f32 v[34:35], v[34:35], v[6:7], v[242:243]
	v_fmac_f32_e32 v36, v32, v32
	v_fmac_f32_e32 v36, v34, v34
	global_store_dwordx4 v[50:51], v[32:35], off offset:192
	v_fmac_f32_e32 v36, v35, v35
	v_add_f32_e32 v36, v40, v36
	v_pk_mul_f32 v[34:35], v[146:147], v[34:35]
	v_pk_mul_f32 v[32:33], v[148:149], v[32:33]
	s_nop 0
	v_cvt_pk_bf16_f32 v32, v32, v33
	v_cvt_pk_bf16_f32 v33, v34, v35
	ds_write_b64 v117, v[32:33] offset:4096
	ds_bpermute_b32 v32, v170, v36
	s_waitcnt lgkmcnt(0)
	v_add_f32_e32 v32, v36, v32
	ds_bpermute_b32 v33, v171, v32
	s_and_saveexec_b64 s[6:7], vcc
	s_cbranch_execz .LBB0_151
	s_waitcnt lgkmcnt(0)
	v_add_f32_e32 v34, v32, v33
	v_lshlrev_b64 v[32:33], 6, v[48:49]
	v_lshl_add_u64 v[32:33], v[144:145], 0, v[32:33]
	global_store_dword v[32:33], v34, off sc1
; DI unsigned pk2(float a, float b) { f32x2 v = {a, b}; bf2_t r = __builtin_convertvector(v, bf2_t); return __builtin_bit_cast(unsigned, r); }
;     static DI void run(const f32x4 (&acc)[8][4], const TileCtx& tc, const Params& p, ldsp_t wb) {
;     ...
;             for (int mm = 0; mm < 4; ++mm) { __builtin_amdgcn_sched_barrier(0);
;                 const int m = h * 4 + mm;
;                 const int row = tc.brow + tc.wr * 128 + m * 16 + tc.fr;
;                 float* xr = xrow_ptr(p, row) + col0;
;                 const float* xs = (EK == 1 && tc.l == 0) ? p.x + (size_t)row * DM + col0 : xr;
;                 float part = 0.f;
; #pragma unroll
;                 for (int n = 0; n < 4; ++n) {
;                     f32x4 xv = *(const f32x4*)(xs + n * 16);
;                     xv += gv[n] * acc[m][n];
;                     *(f32x4*)(xr + n * 16) = xv;
;                     if (has_next) {
;                         part += xv[0] * xv[0] + xv[1] * xv[1] + xv[2] * xv[2] + xv[3] * xv[3];
;                         const f32x4 hv = xv * av[n];
;                         u32x2 w; w[0] = pk2(hv[0], hv[1]); w[1] = pk2(hv[2], hv[3]);
;                         wave_put(wb, mm * 16 + tc.fr, n, tc.fq, w);
;                     }
;                 }
;                 if (has_next) {
;                     part += __shfl_xor(part, 16);
;                     part += __shfl_xor(part, 32);
;                     if (tc.fq == 0) ssp[(size_t)row * 16] = part;
;                 }
;             }
.LBB0_151:
	s_or_b64 exec, exec, s[6:7]
	v_add_u32_e32 v32, 0x70, v132
	v_cmp_gt_i32_e64 s[6:7], s33, v32
	v_add_u32_e32 v34, 0xffffc070, v132
	s_waitcnt lgkmcnt(0)
	v_ashrrev_i32_e32 v33, 31, v32
	v_mov_b32_e32 v36, s71
	v_mov_b32_e32 v37, s55
	v_cndmask_b32_e64 v35, 0, v33, s[6:7]
	v_cndmask_b32_e64 v34, v34, v32, s[6:7]
	v_cndmask_b32_e64 v37, v36, v37, s[6:7]
	v_mov_b32_e32 v36, s70
	v_mov_b32_e32 v38, s54
	v_readlane_b32 s8, v254, 50
	v_cndmask_b32_e64 v36, v36, v38, s[6:7]
	v_lshlrev_b64 v[34:35], 12, v[34:35]
	v_lshlrev_b64 v[38:39], 12, v[32:33]
	v_readlane_b32 s9, v254, 51
	v_lshl_add_u64 v[36:37], v[36:37], 0, v[34:35]
	v_lshl_add_u64 v[34:35], v[36:37], 0, v[150:151]
	v_lshl_add_u64 v[38:39], s[8:9], 0, v[38:39]
	v_cndmask_b32_e64 v37, v37, v39, s[4:5]
	v_cndmask_b32_e64 v36, v36, v38, s[4:5]
	v_lshl_add_u64 v[40:41], v[36:37], 0, v[150:151]
	s_barrier
	global_load_dwordx4 v[36:39], v[40:41], off
	global_load_dwordx4 v[232:235], v[40:41], off offset:64
	global_load_dwordx4 v[236:239], v[40:41], off offset:128
	global_load_dwordx4 v[240:243], v[40:41], off offset:192
	v_readlane_b32 s10, v254, 52
	v_readlane_b32 s11, v254, 53
	v_readlane_b32 s12, v254, 54
	v_readlane_b32 s13, v254, 55
	v_readlane_b32 s14, v254, 56
	v_readlane_b32 s15, v254, 57
	v_readlane_b32 s16, v254, 58
	v_readlane_b32 s17, v254, 59
	v_readlane_b32 s18, v254, 60
	v_readlane_b32 s19, v254, 61
	v_readlane_b32 s20, v254, 62
	v_readlane_b32 s21, v254, 63
	v_readlane_b32 s22, v255, 0
	v_readlane_b32 s23, v255, 1
	s_waitcnt vmcnt(3)
	v_pk_fma_f32 v[16:17], v[16:17], v[28:29], v[36:37]
	s_nop 0
	v_mul_f32_e32 v28, v17, v17
	v_pk_fma_f32 v[18:19], v[18:19], v[30:31], v[38:39]
	v_fmac_f32_e32 v28, v16, v16
	v_fmac_f32_e32 v28, v18, v18
	global_store_dwordx4 v[34:35], v[16:19], off
	v_fmac_f32_e32 v28, v19, v19
	s_nop 0
	v_pk_mul_f32 v[18:19], v[160:161], v[18:19]
	v_pk_mul_f32 v[16:17], v[162:163], v[16:17]
	s_nop 0
	v_cvt_pk_bf16_f32 v16, v16, v17
	v_cvt_pk_bf16_f32 v17, v18, v19
	ds_write_b64 v124, v[16:17] offset:6144
	s_nop 1
	s_waitcnt vmcnt(3)
	v_pk_fma_f32 v[12:13], v[12:13], v[24:25], v[232:233]
	s_nop 0
	v_mul_f32_e32 v16, v13, v13
	v_pk_fma_f32 v[14:15], v[14:15], v[26:27], v[234:235]
	v_fmac_f32_e32 v16, v12, v12
	v_fmac_f32_e32 v16, v14, v14
	global_store_dwordx4 v[34:35], v[12:15], off offset:64
	v_fmac_f32_e32 v16, v15, v15
	v_add_f32_e32 v16, v28, v16
	v_pk_mul_f32 v[14:15], v[156:157], v[14:15]
	v_pk_mul_f32 v[12:13], v[158:159], v[12:13]
	s_nop 0
	v_cvt_pk_bf16_f32 v12, v12, v13
	v_cvt_pk_bf16_f32 v13, v14, v15
	ds_write_b64 v120, v[12:13] offset:6144
	s_nop 1
	s_waitcnt vmcnt(3)
	v_pk_fma_f32 v[8:9], v[8:9], v[20:21], v[236:237]
	s_nop 0
	v_mul_f32_e32 v12, v9, v9
	v_pk_fma_f32 v[10:11], v[10:11], v[22:23], v[238:239]
	v_fmac_f32_e32 v12, v8, v8
	v_fmac_f32_e32 v12, v10, v10
	global_store_dwordx4 v[34:35], v[8:11], off offset:128
	v_fmac_f32_e32 v12, v11, v11
	v_add_f32_e32 v12, v16, v12
	v_pk_mul_f32 v[10:11], v[152:153], v[10:11]
	v_pk_mul_f32 v[8:9], v[154:155], v[8:9]
	s_nop 0
	v_cvt_pk_bf16_f32 v8, v8, v9
	v_cvt_pk_bf16_f32 v9, v10, v11
	ds_write_b64 v116, v[8:9] offset:6144
	s_nop 1
	s_waitcnt vmcnt(3)
	v_pk_fma_f32 v[0:1], v[0:1], v[4:5], v[240:241]
	s_nop 0
	v_mul_f32_e32 v4, v1, v1
	v_pk_fma_f32 v[2:3], v[2:3], v[6:7], v[242:243]
	v_fmac_f32_e32 v4, v0, v0
	v_fmac_f32_e32 v4, v2, v2
	global_store_dwordx4 v[34:35], v[0:3], off offset:192
	v_fmac_f32_e32 v4, v3, v3
	v_add_f32_e32 v4, v12, v4
	v_pk_mul_f32 v[2:3], v[146:147], v[2:3]
	v_pk_mul_f32 v[0:1], v[148:149], v[0:1]
	s_nop 0
	v_cvt_pk_bf16_f32 v0, v0, v1
	v_cvt_pk_bf16_f32 v1, v2, v3
	ds_write_b64 v117, v[0:1] offset:6144
	ds_bpermute_b32 v0, v170, v4
	s_waitcnt lgkmcnt(0)
	v_add_f32_e32 v0, v4, v0
	ds_bpermute_b32 v1, v171, v0
	s_and_saveexec_b64 s[6:7], vcc
	s_cbranch_execz .LBB0_124
	s_waitcnt lgkmcnt(0)
	v_add_f32_e32 v2, v0, v1
	v_lshlrev_b64 v[0:1], 6, v[32:33]
	v_lshl_add_u64 v[0:1], v[144:145], 0, v[0:1]
	global_store_dword v[0:1], v2, off sc1
	s_branch .LBB0_124

; #define WAIT_V0() asm volatile("s_waitcnt vmcnt(0)" ::: "memory")
; #define G_RDA(AF, buf, ks, mh) do { _Pragma("unroll") for (int m = 0; m < 4; ++m) AF[m] = *(const LDSP bf16x8*)(G_SA(buf) + aoff + ((mh) * 4 + m) * 2048 + (ks) * 1024); } while (0)
; #define G_RDB(BF, buf, ks) do { _Pragma("unroll") for (int n = 0; n < 4; ++n) BF[n] = *(const LDSP bf16x8*)(G_SB(buf) + boff + n * 2048 + (ks) * 1024); } while (0)
; #define G_MMA(AF, BF, mh) do { __builtin_amdgcn_s_setprio(1); \
;             _Pragma("unroll") for (int m = 0; m < 4; ++m) _Pragma("unroll") for (int n = 0; n < 4; ++n) \
;                 acc[(mh) * 4 + m][n] = __builtin_amdgcn_mfma_f32_16x16x32_bf16(BF[n], AF[m], acc[(mh) * 4 + m][n], 0, 0, 0); \
;             __builtin_amdgcn_s_setprio(0); } while (0)
; #define G_SB0() __builtin_amdgcn_sched_barrier(0)
; template <int EK>
; DI void gemm_stream(const Params& p, int l, const bf16_t* __restrict__ A, const bf16_t* __restrict__ Bt, int M, int N, int K, ldsp_t shm) {
;     ...
;             G_RDA(Ab_, cur, 0, 1);
;             G_MMA(Aa, Bk0, 0); G_SB0();
;             G_RDA(Aa, cur, 1, 0); G_RDB(Bk1, cur, 1);
;             G_MMA(Ab_, Bk0, 1); G_SB0();
;             G_RDA(Ab_, cur, 1, 1);
;             G_MMA(Aa, Bk1, 0); G_SB0();
;             asm volatile("s_waitcnt lgkmcnt(0)" ::: "memory");
;             WAIT_V0(); __syncthreads();
;         }
;         G_MMA(Ab_, Bk1, 1);
.LBB0_196:
	v_add_u32_e32 v80, 0x12000, v218
	v_add_u32_e32 v84, 0x12800, v218
	v_add_u32_e32 v88, 0x13000, v218
	v_add_u32_e32 v92, 0x13800, v218
	ds_read_b128 v[80:83], v80
	ds_read_b128 v[84:87], v84
	ds_read_b128 v[88:91], v88
	ds_read_b128 v[92:95], v92
	s_setprio 1
	s_waitcnt lgkmcnt(0)
	v_mfma_f32_16x16x32_bf16 v[4:7], v[164:167], v[188:191], v[4:7]
	v_mfma_f32_16x16x32_bf16 v[8:11], v[168:171], v[188:191], v[8:11]
	v_mfma_f32_16x16x32_bf16 v[12:15], v[172:175], v[188:191], v[12:15]
	v_mfma_f32_16x16x32_bf16 v[16:19], v[160:163], v[180:183], v[16:19]
	v_mfma_f32_16x16x32_bf16 v[20:23], v[164:167], v[180:183], v[20:23]
	v_mfma_f32_16x16x32_bf16 v[24:27], v[168:171], v[180:183], v[24:27]
	v_mfma_f32_16x16x32_bf16 v[28:31], v[172:175], v[180:183], v[28:31]
	v_mfma_f32_16x16x32_bf16 v[32:35], v[160:163], v[184:187], v[32:35]
	v_mfma_f32_16x16x32_bf16 v[36:39], v[164:167], v[184:187], v[36:39]
	v_mfma_f32_16x16x32_bf16 v[40:43], v[168:171], v[184:187], v[40:43]
	v_mfma_f32_16x16x32_bf16 v[44:47], v[172:175], v[184:187], v[44:47]
	v_mfma_f32_16x16x32_bf16 v[48:51], v[160:163], v[176:179], v[48:51]
	v_mfma_f32_16x16x32_bf16 v[52:55], v[164:167], v[176:179], v[52:55]
	v_mfma_f32_16x16x32_bf16 v[56:59], v[168:171], v[176:179], v[56:59]
	v_mfma_f32_16x16x32_bf16 v[60:63], v[172:175], v[176:179], v[60:63]
	v_mfma_f32_16x16x32_bf16 v[0:3], v[160:163], v[188:191], v[0:3]
	s_setprio 0
	v_add_u32_e32 v144, 0x10400, v218
	v_add_u32_e32 v148, 0x10c00, v218
	v_add_u32_e32 v152, 0x11400, v218
	v_add_u32_e32 v156, 0x11c00, v218
	v_add_u32_e32 v176, 0x18400, v219
	v_add_u32_e32 v180, 0x18c00, v219
	v_add_u32_e32 v184, 0x19400, v219
	v_add_u32_e32 v188, 0x19c00, v219
	ds_read_b128 v[144:147], v144
	ds_read_b128 v[148:151], v148
	ds_read_b128 v[152:155], v152
	ds_read_b128 v[156:159], v156
	ds_read_b128 v[176:179], v176
	ds_read_b128 v[180:183], v180
	ds_read_b128 v[184:187], v184
	ds_read_b128 v[188:191], v188
	s_setprio 1
	v_mfma_f32_16x16x32_bf16 v[140:143], v[160:163], v[80:83], v[140:143]
	v_mfma_f32_16x16x32_bf16 v[194:197], v[164:167], v[80:83], v[136:139]
	v_mfma_f32_16x16x32_bf16 v[198:201], v[168:171], v[80:83], v[132:135]
	v_mfma_f32_16x16x32_bf16 v[204:207], v[172:175], v[80:83], v[128:131]
	v_mfma_f32_16x16x32_bf16 v[210:213], v[160:163], v[84:87], v[124:127]
	v_mfma_f32_16x16x32_bf16 v[214:217], v[164:167], v[84:87], v[120:123]
	v_mfma_f32_16x16x32_bf16 v[220:223], v[168:171], v[84:87], v[116:119]
	v_mfma_f32_16x16x32_bf16 v[224:227], v[172:175], v[84:87], v[112:115]
	v_mfma_f32_16x16x32_bf16 v[228:231], v[160:163], v[88:91], v[108:111]
	v_mfma_f32_16x16x32_bf16 v[232:235], v[164:167], v[88:91], v[104:107]
	v_mfma_f32_16x16x32_bf16 v[236:239], v[168:171], v[88:91], v[100:103]
	v_mfma_f32_16x16x32_bf16 v[240:243], v[172:175], v[88:91], v[96:99]
	v_mfma_f32_16x16x32_bf16 v[160:163], v[160:163], v[92:95], v[64:67]
	v_mfma_f32_16x16x32_bf16 v[164:167], v[164:167], v[92:95], v[68:71]
	v_mfma_f32_16x16x32_bf16 v[168:171], v[168:171], v[92:95], v[72:75]
	v_mfma_f32_16x16x32_bf16 v[172:175], v[172:175], v[92:95], v[76:79]
	s_setprio 0
	v_add_u32_e32 v64, 0x12400, v218
	v_add_u32_e32 v68, 0x12c00, v218
	ds_read_b128 v[64:67], v64
	ds_read_b128 v[244:247], v68
	v_add_u32_e32 v68, 0x13400, v218
	v_add_u32_e32 v69, 0x13c00, v218
	ds_read_b128 v[248:251], v68
	ds_read_b128 v[68:71], v69
	s_setprio 1
	s_waitcnt lgkmcnt(0)
	v_mfma_f32_16x16x32_bf16 v[136:139], v[180:183], v[144:147], v[4:7]
	v_mfma_f32_16x16x32_bf16 v[132:135], v[184:187], v[144:147], v[8:11]
	v_mfma_f32_16x16x32_bf16 v[128:131], v[188:191], v[144:147], v[12:15]
	v_mfma_f32_16x16x32_bf16 v[124:127], v[176:179], v[148:151], v[16:19]
	v_mfma_f32_16x16x32_bf16 v[120:123], v[180:183], v[148:151], v[20:23]
	v_mfma_f32_16x16x32_bf16 v[116:119], v[184:187], v[148:151], v[24:27]
	v_mfma_f32_16x16x32_bf16 v[112:115], v[188:191], v[148:151], v[28:31]
	v_mfma_f32_16x16x32_bf16 v[108:111], v[176:179], v[152:155], v[32:35]
	v_mfma_f32_16x16x32_bf16 v[104:107], v[180:183], v[152:155], v[36:39]
	v_mfma_f32_16x16x32_bf16 v[100:103], v[184:187], v[152:155], v[40:43]
	v_mfma_f32_16x16x32_bf16 v[96:99], v[188:191], v[152:155], v[44:47]
	v_mfma_f32_16x16x32_bf16 v[92:95], v[176:179], v[156:159], v[48:51]
	v_mfma_f32_16x16x32_bf16 v[88:91], v[180:183], v[156:159], v[52:55]
	v_mfma_f32_16x16x32_bf16 v[84:87], v[184:187], v[156:159], v[56:59]
	v_mfma_f32_16x16x32_bf16 v[80:83], v[188:191], v[156:159], v[60:63]
	v_mfma_f32_16x16x32_bf16 v[0:3], v[176:179], v[144:147], v[0:3]
	s_setprio 0
	s_waitcnt lgkmcnt(0)
	s_waitcnt vmcnt(0)
	s_waitcnt vmcnt(0)
	s_barrier
; #define G_MMA(AF, BF, mh) do { __builtin_amdgcn_s_setprio(1); \
;             _Pragma("unroll") for (int m = 0; m < 4; ++m) _Pragma("unroll") for (int n = 0; n < 4; ++n) \
;                 acc[(mh) * 4 + m][n] = __builtin_amdgcn_mfma_f32_16x16x32_bf16(BF[n], AF[m], acc[(mh) * 4 + m][n], 0, 0, 0); \
;             __builtin_amdgcn_s_setprio(0); } while (0)
;     static DI void run(const f32x4 (&acc)[8][4], const TileCtx& tc, const Params& p, ldsp_t wb) {
;     ...
;         const int cond = tc.brow < NLAT ? (tc.brow >> 12) : 4;
;         const float* gate = p.mod + ((size_t)tc.l * 5 + cond) * 6144 + GI * DM;
;         const int col0 = tc.bcol + tc.wc * 64 + tc.fq * 4;
;         const bool has_next = EK == 1 || tc.l + 1 < DEPTH;
;         const int ln = EK == 1 ? tc.l : (has_next ? tc.l + 1 : tc.l);
;         const float* gnx = (EK == 1 ? p.norm2_g : p.norm1_g) + (size_t)ln * DM + col0;
;         const float* scn = p.mod + ((size_t)ln * 5 + cond) * 6144 + (EK == 1 ? 4 : 1) * DM + col0;
;         float* ssp = p.ss + (size_t)(ln * 2 + (EK == 1 ? 1 : 0)) * NTOK * 16 + (tc.bcol >> 8) * 4 + tc.wc;
;         f32x4 gv[4], av[4];
; #pragma unroll
;         for (int n = 0; n < 4; ++n) {
;             gv[n] = *(const f32x4*)(gate + col0 + n * 16);
;             const f32x4 g1 = *(const f32x4*)(gnx + n * 16), s1 = *(const f32x4*)(scn + n * 16);
;             av[n] = g1 * (1.f + s1);
;         }
; #pragma unroll
;         for (int h = 0; h < 2; ++h) {
; #pragma unroll
;             for (int mm = 0; mm < 4; ++mm) { __builtin_amdgcn_sched_barrier(0);
;                 const int m = h * 4 + mm;
;                 const int row = tc.brow + tc.wr * 128 + m * 16 + tc.fr;
;                 float* xr = xrow_ptr(p, row) + col0;
;                 const float* xs = (EK == 1 && tc.l == 0) ? p.x + (size_t)row * DM + col0 : xr;
;                 float part = 0.f;
; #pragma unroll
;                 for (int n = 0; n < 4; ++n) {
;                     f32x4 xv = *(const f32x4*)(xs + n * 16);
;                     xv += gv[n] * acc[m][n];
;                     *(f32x4*)(xr + n * 16) = xv;
; template <int EK>
; DI void gemm_stream(const Params& p, int l, const bf16_t* __restrict__ A, const bf16_t* __restrict__ Bt, int M, int N, int K, ldsp_t shm) {
;     ...
;         G_MMA(Ab_, Bk1, 1);
	s_setprio 1
	v_mfma_f32_16x16x32_bf16 v[76:79], v[176:179], v[64:67], v[140:143]
	v_mfma_f32_16x16x32_bf16 v[72:75], v[180:183], v[64:67], v[194:197]
	v_mfma_f32_16x16x32_bf16 v[194:197], v[184:187], v[64:67], v[198:201]
	v_mfma_f32_16x16x32_bf16 v[64:67], v[188:191], v[64:67], v[204:207]
	v_mfma_f32_16x16x32_bf16 v[60:63], v[176:179], v[244:247], v[210:213]
	v_mfma_f32_16x16x32_bf16 v[56:59], v[180:183], v[244:247], v[214:217]
	v_mfma_f32_16x16x32_bf16 v[52:55], v[184:187], v[244:247], v[220:223]
	v_mfma_f32_16x16x32_bf16 v[48:51], v[188:191], v[244:247], v[224:227]
	v_mfma_f32_16x16x32_bf16 v[44:47], v[176:179], v[248:251], v[228:231]
	v_mfma_f32_16x16x32_bf16 v[40:43], v[180:183], v[248:251], v[232:235]
	v_mfma_f32_16x16x32_bf16 v[36:39], v[184:187], v[248:251], v[236:239]
	v_mfma_f32_16x16x32_bf16 v[32:35], v[188:191], v[248:251], v[240:243]
	v_mfma_f32_16x16x32_bf16 v[24:27], v[176:179], v[68:71], v[160:163]
	v_mfma_f32_16x16x32_bf16 v[16:19], v[180:183], v[68:71], v[164:167]
	v_mfma_f32_16x16x32_bf16 v[8:11], v[184:187], v[68:71], v[168:171]
	v_mfma_f32_16x16x32_bf16 v[68:71], v[188:191], v[68:71], v[172:175]
	s_setprio 0
	v_mov_b32_e32 v179, v252
	s_lshl_b32 s43, s45, 8
	s_min_i32 s4, s43, 0x4000
	s_ashr_i32 s35, s4, 12
	s_lshl_b32 s34, s44, 8
	s_ashr_i32 s45, s35, 31
	s_mul_i32 s4, s48, 5
	s_add_u32 s4, s4, s35
	s_mul_hi_i32 s5, s48, 5
	v_ashrrev_i32_e32 v186, 6, v179
	s_addc_u32 s5, s5, s45
	v_mov_b64_e32 v[4:5], s[66:67]
	v_mov_b32_e32 v13, 0x6000
	v_and_b32_e32 v190, 3, v186
	v_bfe_u32 v189, v179, 4, 2
	s_mul_i32 s47, s5, 0x6000
	v_mad_u64_u32 v[6:7], s[4:5], s4, v13, v[4:5]
	v_lshlrev_b32_e32 v184, 6, v190
	v_lshlrev_b32_e32 v12, 2, v189
	s_add_u32 s4, s98, s35
	v_or3_b32 v176, v12, s34, v184
	s_addc_u32 s5, s93, s45
	v_ashrrev_i32_e32 v177, 31, v176
	s_mul_i32 s35, s5, 0x6000
	v_mad_u64_u32 v[4:5], s[4:5], s4, v13, v[4:5]
	v_lshlrev_b64 v[168:169], 2, v[176:177]
	v_add_u32_e32 v5, s35, v5
	v_add_u32_e32 v7, s47, v7
	v_lshl_add_u64 v[4:5], v[4:5], 0, v[168:169]
	s_mov_b64 s[4:5], 0x1000
	v_lshl_add_u64 v[144:145], v[4:5], 0, s[4:5]
	v_lshl_add_u64 v[6:7], v[6:7], 0, v[168:169]
	s_mov_b64 s[4:5], 0x5000
	v_lshl_add_u64 v[22:23], v[6:7], 0, s[4:5]
	s_movk_i32 s4, 0x5000
	v_add_co_u32_e32 v6, vcc, s4, v6
	v_lshl_add_u64 v[20:21], s[38:39], 0, v[168:169]
	s_nop 0
	v_addc_co_u32_e32 v7, vcc, 0, v7, vcc
	v_add_co_u32_e32 v4, vcc, s29, v4
	s_lshl_b32 s4, s44, 2
	s_nop 0
	v_addc_co_u32_e32 v5, vcc, 0, v5, vcc
	global_load_dwordx4 v[28:31], v[6:7], off
	global_load_dwordx4 v[172:175], v[4:5], off
	global_load_dwordx4 v[164:167], v[20:21], off
	global_load_dwordx4 v[156:159], v[20:21], off offset:64
	global_load_dwordx4 v[160:163], v[144:145], off offset:64
	global_load_dwordx4 v[152:155], v[144:145], off offset:128
	global_load_dwordx4 v[12:15], v[22:23], off offset:128
	global_load_dwordx4 v[4:7], v[22:23], off offset:192
	global_load_dwordx4 v[148:151], v[20:21], off offset:128
	global_load_dwordx4 v[140:143], v[20:21], off offset:192
	s_nop 0
	global_load_dwordx4 v[20:23], v[22:23], off offset:64
	s_nop 0
	global_load_dwordx4 v[144:147], v[144:145], off offset:192
	s_ashr_i32 s5, s4, 31
	s_lshl_b64 s[4:5], s[4:5], 2
	s_add_u32 s4, s10, s4
	v_and_b32_e32 v187, 15, v179
	s_addc_u32 s5, s11, s5
	v_ashrrev_i32_e32 v170, 1, v179
	v_and_b32_e32 v188, 0xffffff80, v170
	v_add_u32_e32 v178, s43, v188
	v_or_b32_e32 v180, v178, v187
	v_add_u32_e32 v170, 0xffffc000, v180
	v_ashrrev_i32_e32 v181, 31, v180
	v_cmp_gt_i32_e32 vcc, s33, v180
	v_mov_b32_e32 v182, s71
	v_mov_b32_e32 v183, s55
	v_cndmask_b32_e32 v171, 0, v181, vcc
	v_cndmask_b32_e32 v170, v170, v180, vcc
	v_cndmask_b32_e32 v183, v182, v183, vcc
	v_mov_b32_e32 v182, s70
	v_mov_b32_e32 v185, s54
	v_cndmask_b32_e32 v182, v182, v185, vcc
	v_lshlrev_b64 v[170:171], 12, v[170:171]
	v_lshl_add_u64 v[170:171], v[182:183], 0, v[170:171]
	v_lshl_add_u64 v[182:183], v[170:171], 0, v[168:169]
	s_barrier
	global_load_dwordx4 v[168:171], v[182:183], off
	global_load_dwordx4 v[232:235], v[182:183], off offset:64
	global_load_dwordx4 v[236:239], v[182:183], off offset:128
	global_load_dwordx4 v[240:243], v[182:183], off offset:192
	s_mov_b64 s[44:45], -1
	s_and_b64 vcc, exec, s[36:37]
	s_waitcnt vmcnt(3)
	v_pk_fma_f32 v[170:171], v[2:3], v[30:31], v[170:171]
	v_pk_fma_f32 v[168:169], v[0:1], v[28:29], v[168:169]
	global_store_dwordx4 v[182:183], v[168:171], off
	s_cbranch_vccz .LBB0_198
	s_nop 1
	s_mov_b64 s[44:45], 0
	s_waitcnt vmcnt(3)
	v_pk_fma_f32 v[2:3], v[138:139], v[22:23], v[234:235]
	v_pk_fma_f32 v[0:1], v[136:137], v[20:21], v[232:233]
	global_store_dwordx4 v[182:183], v[0:3], off offset:64
	s_nop 1
	s_waitcnt vmcnt(3)
	v_pk_fma_f32 v[2:3], v[134:135], v[14:15], v[238:239]
	v_pk_fma_f32 v[0:1], v[132:133], v[12:13], v[236:237]
	global_store_dwordx4 v[182:183], v[0:3], off offset:128
	s_nop 1
	s_waitcnt vmcnt(3)
	v_pk_fma_f32 v[2:3], v[130:131], v[6:7], v[242:243]
	v_pk_fma_f32 v[0:1], v[128:129], v[4:5], v[240:241]
	global_store_dwordx4 v[182:183], v[0:3], off offset:192

;     static DI void run(const f32x4 (&acc)[8][4], const TileCtx& tc, const Params& p, ldsp_t wb) {
;     ...
;             for (int mm = 0; mm < 4; ++mm) { __builtin_amdgcn_sched_barrier(0);
;                 const int m = h * 4 + mm;
;                 const int row = tc.brow + tc.wr * 128 + m * 16 + tc.fr;
;                 float* xr = xrow_ptr(p, row) + col0;
;                 const float* xs = (EK == 1 && tc.l == 0) ? p.x + (size_t)row * DM + col0 : xr;
;                 float part = 0.f;
; #pragma unroll
;                 for (int n = 0; n < 4; ++n) {
;                     f32x4 xv = *(const f32x4*)(xs + n * 16);
;                     xv += gv[n] * acc[m][n];
;                     *(f32x4*)(xr + n * 16) = xv;
.LBB0_202:
	v_or_b32_e32 v0, s43, v187
	v_add_u32_e32 v132, v188, v0
	v_add_u32_e32 v128, 16, v132
	v_add_u32_e32 v0, 0xffffc010, v132
	s_waitcnt lgkmcnt(0)
	v_ashrrev_i32_e32 v129, 31, v128
	v_cmp_gt_i32_e32 vcc, s33, v128
	v_mov_b32_e32 v2, s71
	v_mov_b32_e32 v3, s55
	v_cndmask_b32_e32 v1, 0, v129, vcc
	v_cndmask_b32_e32 v0, v0, v128, vcc
	v_cndmask_b32_e32 v3, v2, v3, vcc
	v_mov_b32_e32 v2, s70
	v_mov_b32_e32 v130, s54
	v_cndmask_b32_e32 v2, v2, v130, vcc
	v_lshlrev_b64 v[0:1], 12, v[0:1]
	v_lshl_add_u64 v[0:1], v[2:3], 0, v[0:1]
	v_lshl_add_u64 v[130:131], v[176:177], 2, v[0:1]
	s_barrier
	global_load_dwordx4 v[0:3], v[130:131], off
	global_load_dwordx4 v[232:235], v[130:131], off offset:64
	global_load_dwordx4 v[236:239], v[130:131], off offset:128
	global_load_dwordx4 v[240:243], v[130:131], off offset:192
	s_mov_b64 s[4:5], -1
	s_and_b64 vcc, exec, s[36:37]
	s_waitcnt vmcnt(3)
	v_pk_fma_f32 v[126:127], v[126:127], v[30:31], v[2:3]
	v_pk_fma_f32 v[124:125], v[124:125], v[28:29], v[0:1]
	global_store_dwordx4 v[130:131], v[124:127], off
	s_cbranch_vccz .LBB0_204
	s_nop 1
	s_mov_b64 s[4:5], 0
	s_waitcnt vmcnt(3)
	v_pk_fma_f32 v[2:3], v[122:123], v[22:23], v[234:235]
	v_pk_fma_f32 v[0:1], v[120:121], v[20:21], v[232:233]
	global_store_dwordx4 v[130:131], v[0:3], off offset:64
	s_nop 1
	s_waitcnt vmcnt(3)
	v_pk_fma_f32 v[2:3], v[118:119], v[14:15], v[238:239]
	v_pk_fma_f32 v[0:1], v[116:117], v[12:13], v[236:237]
	global_store_dwordx4 v[130:131], v[0:3], off offset:128
	s_nop 1
	s_waitcnt vmcnt(3)
	v_pk_fma_f32 v[2:3], v[114:115], v[6:7], v[242:243]
	v_pk_fma_f32 v[0:1], v[112:113], v[4:5], v[240:241]
	global_store_dwordx4 v[130:131], v[0:3], off offset:192

;     static DI void run(const f32x4 (&acc)[8][4], const TileCtx& tc, const Params& p, ldsp_t wb) {
;     ...
;             for (int mm = 0; mm < 4; ++mm) { __builtin_amdgcn_sched_barrier(0);
;                 const int m = h * 4 + mm;
;                 const int row = tc.brow + tc.wr * 128 + m * 16 + tc.fr;
;                 float* xr = xrow_ptr(p, row) + col0;
;                 const float* xs = (EK == 1 && tc.l == 0) ? p.x + (size_t)row * DM + col0 : xr;
;                 float part = 0.f;
; #pragma unroll
;                 for (int n = 0; n < 4; ++n) {
;                     f32x4 xv = *(const f32x4*)(xs + n * 16);
;                     xv += gv[n] * acc[m][n];
;                     *(f32x4*)(xr + n * 16) = xv;
.LBB0_208:
	v_add_u32_e32 v112, 32, v132
	v_add_u32_e32 v0, 0xffffc020, v132
	s_waitcnt lgkmcnt(0)
	v_ashrrev_i32_e32 v113, 31, v112
	v_cmp_gt_i32_e32 vcc, s33, v112
	v_mov_b32_e32 v2, s71
	v_mov_b32_e32 v3, s55
	v_cndmask_b32_e32 v1, 0, v113, vcc
	v_cndmask_b32_e32 v0, v0, v112, vcc
	v_cndmask_b32_e32 v3, v2, v3, vcc
	v_mov_b32_e32 v2, s70
	v_mov_b32_e32 v114, s54
	v_cndmask_b32_e32 v2, v2, v114, vcc
	v_lshlrev_b64 v[0:1], 12, v[0:1]
	v_lshl_add_u64 v[0:1], v[2:3], 0, v[0:1]
	v_lshl_add_u64 v[114:115], v[176:177], 2, v[0:1]
	s_barrier
	global_load_dwordx4 v[0:3], v[114:115], off
	global_load_dwordx4 v[232:235], v[114:115], off offset:64
	global_load_dwordx4 v[236:239], v[114:115], off offset:128
	global_load_dwordx4 v[240:243], v[114:115], off offset:192
	s_mov_b64 s[4:5], -1
	s_and_b64 vcc, exec, s[36:37]
	s_waitcnt vmcnt(3)
	v_pk_fma_f32 v[110:111], v[110:111], v[30:31], v[2:3]
	v_pk_fma_f32 v[108:109], v[108:109], v[28:29], v[0:1]
	global_store_dwordx4 v[114:115], v[108:111], off
	s_cbranch_vccz .LBB0_210
	s_nop 1
	s_mov_b64 s[4:5], 0
	s_waitcnt vmcnt(3)
	v_pk_fma_f32 v[2:3], v[106:107], v[22:23], v[234:235]
	v_pk_fma_f32 v[0:1], v[104:105], v[20:21], v[232:233]
	global_store_dwordx4 v[114:115], v[0:3], off offset:64
	s_nop 1
	s_waitcnt vmcnt(3)
	v_pk_fma_f32 v[2:3], v[102:103], v[14:15], v[238:239]
	v_pk_fma_f32 v[0:1], v[100:101], v[12:13], v[236:237]
	global_store_dwordx4 v[114:115], v[0:3], off offset:128
	s_nop 1
	s_waitcnt vmcnt(3)
	v_pk_fma_f32 v[2:3], v[98:99], v[6:7], v[242:243]
	v_pk_fma_f32 v[0:1], v[96:97], v[4:5], v[240:241]
	global_store_dwordx4 v[114:115], v[0:3], off offset:192

;     static DI void run(const f32x4 (&acc)[8][4], const TileCtx& tc, const Params& p, ldsp_t wb) {
;     ...
;             for (int mm = 0; mm < 4; ++mm) { __builtin_amdgcn_sched_barrier(0);
;                 const int m = h * 4 + mm;
;                 const int row = tc.brow + tc.wr * 128 + m * 16 + tc.fr;
;                 float* xr = xrow_ptr(p, row) + col0;
;                 const float* xs = (EK == 1 && tc.l == 0) ? p.x + (size_t)row * DM + col0 : xr;
;                 float part = 0.f;
; #pragma unroll
;                 for (int n = 0; n < 4; ++n) {
;                     f32x4 xv = *(const f32x4*)(xs + n * 16);
;                     xv += gv[n] * acc[m][n];
;                     *(f32x4*)(xr + n * 16) = xv;
.LBB0_214:
	v_add_u32_e32 v96, 48, v132
	v_add_u32_e32 v0, 0xffffc030, v132
	s_waitcnt lgkmcnt(0)
	v_ashrrev_i32_e32 v97, 31, v96
	v_cmp_gt_i32_e32 vcc, s33, v96
	v_mov_b32_e32 v2, s71
	v_mov_b32_e32 v3, s55
	v_cndmask_b32_e32 v1, 0, v97, vcc
	v_cndmask_b32_e32 v0, v0, v96, vcc
	v_cndmask_b32_e32 v3, v2, v3, vcc
	v_mov_b32_e32 v2, s70
	v_mov_b32_e32 v98, s54
	v_cndmask_b32_e32 v2, v2, v98, vcc
	v_lshlrev_b64 v[0:1], 12, v[0:1]
	v_lshl_add_u64 v[0:1], v[2:3], 0, v[0:1]
	v_lshl_add_u64 v[98:99], v[176:177], 2, v[0:1]
	s_barrier
	global_load_dwordx4 v[0:3], v[98:99], off
	global_load_dwordx4 v[232:235], v[98:99], off offset:64
	global_load_dwordx4 v[236:239], v[98:99], off offset:128
	global_load_dwordx4 v[240:243], v[98:99], off offset:192
	s_mov_b64 s[4:5], -1
	s_and_b64 vcc, exec, s[36:37]
	s_waitcnt vmcnt(3)
	v_pk_fma_f32 v[94:95], v[94:95], v[30:31], v[2:3]
	v_pk_fma_f32 v[92:93], v[92:93], v[28:29], v[0:1]
	global_store_dwordx4 v[98:99], v[92:95], off
	s_cbranch_vccz .LBB0_216
	s_nop 1
	s_mov_b64 s[4:5], 0
	s_waitcnt vmcnt(3)
	v_pk_fma_f32 v[2:3], v[90:91], v[22:23], v[234:235]
	v_pk_fma_f32 v[0:1], v[88:89], v[20:21], v[232:233]
	global_store_dwordx4 v[98:99], v[0:3], off offset:64
	s_nop 1
	s_waitcnt vmcnt(3)
	v_pk_fma_f32 v[2:3], v[86:87], v[14:15], v[238:239]
	v_pk_fma_f32 v[0:1], v[84:85], v[12:13], v[236:237]
	global_store_dwordx4 v[98:99], v[0:3], off offset:128
	s_nop 1
	s_waitcnt vmcnt(3)
	v_pk_fma_f32 v[2:3], v[82:83], v[6:7], v[242:243]
	v_pk_fma_f32 v[0:1], v[80:81], v[4:5], v[240:241]
	global_store_dwordx4 v[98:99], v[0:3], off offset:192

;     static DI void run(const f32x4 (&acc)[8][4], const TileCtx& tc, const Params& p, ldsp_t wb) {
;     ...
;             for (int mm = 0; mm < 4; ++mm) { __builtin_amdgcn_sched_barrier(0);
;                 const int m = h * 4 + mm;
;                 const int row = tc.brow + tc.wr * 128 + m * 16 + tc.fr;
;                 float* xr = xrow_ptr(p, row) + col0;
;                 const float* xs = (EK == 1 && tc.l == 0) ? p.x + (size_t)row * DM + col0 : xr;
;                 float part = 0.f;
; #pragma unroll
;                 for (int n = 0; n < 4; ++n) {
;                     f32x4 xv = *(const f32x4*)(xs + n * 16);
;                     xv += gv[n] * acc[m][n];
;                     *(f32x4*)(xr + n * 16) = xv;
.LBB0_220:
	v_add3_u32 v80, v188, s43, 64
	v_or_b32_e32 v82, v80, v187
	v_add_u32_e32 v0, 0xffffc000, v82
	v_ashrrev_i32_e32 v83, 31, v82
	v_cmp_gt_i32_e32 vcc, s33, v82
	v_mov_b32_e32 v2, s71
	v_mov_b32_e32 v3, s55
	v_cndmask_b32_e32 v1, 0, v83, vcc
	v_cndmask_b32_e32 v0, v0, v82, vcc
	v_cndmask_b32_e32 v3, v2, v3, vcc
	v_mov_b32_e32 v2, s70
	v_mov_b32_e32 v81, s54
	v_cndmask_b32_e32 v2, v2, v81, vcc
	v_lshlrev_b64 v[0:1], 12, v[0:1]
	v_lshl_add_u64 v[0:1], v[2:3], 0, v[0:1]
	v_lshl_add_u64 v[84:85], v[176:177], 2, v[0:1]
	s_barrier
	global_load_dwordx4 v[0:3], v[84:85], off
	global_load_dwordx4 v[232:235], v[84:85], off offset:64
	global_load_dwordx4 v[236:239], v[84:85], off offset:128
	global_load_dwordx4 v[240:243], v[84:85], off offset:192
	s_mov_b64 s[4:5], -1
	s_and_b64 vcc, exec, s[36:37]
	s_waitcnt vmcnt(3)
	v_pk_fma_f32 v[78:79], v[78:79], v[30:31], v[2:3]
	v_pk_fma_f32 v[76:77], v[76:77], v[28:29], v[0:1]
	global_store_dwordx4 v[84:85], v[76:79], off
	s_cbranch_vccz .LBB0_222
	s_nop 1
	s_mov_b64 s[4:5], 0
	s_waitcnt vmcnt(3)
	v_pk_fma_f32 v[2:3], v[74:75], v[22:23], v[234:235]
	v_pk_fma_f32 v[0:1], v[72:73], v[20:21], v[232:233]
	global_store_dwordx4 v[84:85], v[0:3], off offset:64
	s_nop 1
	s_waitcnt vmcnt(3)
	v_pk_fma_f32 v[2:3], v[196:197], v[14:15], v[238:239]
	v_pk_fma_f32 v[0:1], v[194:195], v[12:13], v[236:237]
	global_store_dwordx4 v[84:85], v[0:3], off offset:128
	s_nop 1
	s_waitcnt vmcnt(3)
	v_pk_fma_f32 v[2:3], v[66:67], v[6:7], v[242:243]
	v_pk_fma_f32 v[0:1], v[64:65], v[4:5], v[240:241]
	global_store_dwordx4 v[84:85], v[0:3], off offset:192

;     static DI void run(const f32x4 (&acc)[8][4], const TileCtx& tc, const Params& p, ldsp_t wb) {
;     ...
;             for (int mm = 0; mm < 4; ++mm) { __builtin_amdgcn_sched_barrier(0);
;                 const int m = h * 4 + mm;
;                 const int row = tc.brow + tc.wr * 128 + m * 16 + tc.fr;
;                 float* xr = xrow_ptr(p, row) + col0;
;                 const float* xs = (EK == 1 && tc.l == 0) ? p.x + (size_t)row * DM + col0 : xr;
;                 float part = 0.f;
; #pragma unroll
;                 for (int n = 0; n < 4; ++n) {
;                     f32x4 xv = *(const f32x4*)(xs + n * 16);
;                     xv += gv[n] * acc[m][n];
;                     *(f32x4*)(xr + n * 16) = xv;
.LBB0_226:
	v_add_u32_e32 v64, 0x50, v132
	v_add_u32_e32 v0, 0xffffc050, v132
	s_waitcnt lgkmcnt(0)
	v_ashrrev_i32_e32 v65, 31, v64
	v_cmp_gt_i32_e32 vcc, s33, v64
	v_mov_b32_e32 v2, s71
	v_mov_b32_e32 v3, s55
	v_cndmask_b32_e32 v1, 0, v65, vcc
	v_cndmask_b32_e32 v0, v0, v64, vcc
	v_cndmask_b32_e32 v3, v2, v3, vcc
	v_mov_b32_e32 v2, s70
	v_mov_b32_e32 v66, s54
	v_cndmask_b32_e32 v2, v2, v66, vcc
	v_lshlrev_b64 v[0:1], 12, v[0:1]
	v_lshl_add_u64 v[0:1], v[2:3], 0, v[0:1]
	v_lshl_add_u64 v[66:67], v[176:177], 2, v[0:1]
	s_barrier
	global_load_dwordx4 v[0:3], v[66:67], off
	global_load_dwordx4 v[232:235], v[66:67], off offset:64
	global_load_dwordx4 v[236:239], v[66:67], off offset:128
	global_load_dwordx4 v[240:243], v[66:67], off offset:192
	s_mov_b64 s[4:5], -1
	s_and_b64 vcc, exec, s[36:37]
	s_waitcnt vmcnt(3)
	v_pk_fma_f32 v[62:63], v[62:63], v[30:31], v[2:3]
	v_pk_fma_f32 v[60:61], v[60:61], v[28:29], v[0:1]
	global_store_dwordx4 v[66:67], v[60:63], off
	s_cbranch_vccz .LBB0_228
	s_nop 1
	s_mov_b64 s[4:5], 0
	s_waitcnt vmcnt(3)
	v_pk_fma_f32 v[2:3], v[58:59], v[22:23], v[234:235]
	v_pk_fma_f32 v[0:1], v[56:57], v[20:21], v[232:233]
	global_store_dwordx4 v[66:67], v[0:3], off offset:64
	s_nop 1
	s_waitcnt vmcnt(3)
	v_pk_fma_f32 v[2:3], v[54:55], v[14:15], v[238:239]
	v_pk_fma_f32 v[0:1], v[52:53], v[12:13], v[236:237]
	global_store_dwordx4 v[66:67], v[0:3], off offset:128
	s_nop 1
	s_waitcnt vmcnt(3)
	v_pk_fma_f32 v[2:3], v[50:51], v[6:7], v[242:243]
	v_pk_fma_f32 v[0:1], v[48:49], v[4:5], v[240:241]
	global_store_dwordx4 v[66:67], v[0:3], off offset:192

;     static DI void run(const f32x4 (&acc)[8][4], const TileCtx& tc, const Params& p, ldsp_t wb) {
;     ...
;             for (int mm = 0; mm < 4; ++mm) { __builtin_amdgcn_sched_barrier(0);
;                 const int m = h * 4 + mm;
;                 const int row = tc.brow + tc.wr * 128 + m * 16 + tc.fr;
;                 float* xr = xrow_ptr(p, row) + col0;
;                 const float* xs = (EK == 1 && tc.l == 0) ? p.x + (size_t)row * DM + col0 : xr;
;                 float part = 0.f;
; #pragma unroll
;                 for (int n = 0; n < 4; ++n) {
;                     f32x4 xv = *(const f32x4*)(xs + n * 16);
;                     xv += gv[n] * acc[m][n];
;                     *(f32x4*)(xr + n * 16) = xv;
.LBB0_232:
	v_add_u32_e32 v48, 0x60, v132
	v_add_u32_e32 v0, 0xffffc060, v132
	s_waitcnt lgkmcnt(0)
	v_ashrrev_i32_e32 v49, 31, v48
	v_cmp_gt_i32_e32 vcc, s33, v48
	v_mov_b32_e32 v2, s71
	v_mov_b32_e32 v3, s55
	v_cndmask_b32_e32 v1, 0, v49, vcc
	v_cndmask_b32_e32 v0, v0, v48, vcc
	v_cndmask_b32_e32 v3, v2, v3, vcc
	v_mov_b32_e32 v2, s70
	v_mov_b32_e32 v50, s54
	v_cndmask_b32_e32 v2, v2, v50, vcc
	v_lshlrev_b64 v[0:1], 12, v[0:1]
	v_lshl_add_u64 v[0:1], v[2:3], 0, v[0:1]
	v_lshl_add_u64 v[50:51], v[176:177], 2, v[0:1]
	s_barrier
	global_load_dwordx4 v[0:3], v[50:51], off
	global_load_dwordx4 v[232:235], v[50:51], off offset:64
	global_load_dwordx4 v[236:239], v[50:51], off offset:128
	global_load_dwordx4 v[240:243], v[50:51], off offset:192
	s_mov_b64 s[4:5], -1
	s_and_b64 vcc, exec, s[36:37]
	s_waitcnt vmcnt(3)
	v_pk_fma_f32 v[46:47], v[46:47], v[30:31], v[2:3]
	v_pk_fma_f32 v[44:45], v[44:45], v[28:29], v[0:1]
	global_store_dwordx4 v[50:51], v[44:47], off
	s_cbranch_vccz .LBB0_234
	s_nop 1
	s_mov_b64 s[4:5], 0
	s_waitcnt vmcnt(3)
	v_pk_fma_f32 v[2:3], v[42:43], v[22:23], v[234:235]
	v_pk_fma_f32 v[0:1], v[40:41], v[20:21], v[232:233]
	global_store_dwordx4 v[50:51], v[0:3], off offset:64
	s_nop 1
	s_waitcnt vmcnt(3)
	v_pk_fma_f32 v[2:3], v[38:39], v[14:15], v[238:239]
	v_pk_fma_f32 v[0:1], v[36:37], v[12:13], v[236:237]
	global_store_dwordx4 v[50:51], v[0:3], off offset:128
	s_nop 1
	s_waitcnt vmcnt(3)
	v_pk_fma_f32 v[2:3], v[34:35], v[6:7], v[242:243]
	v_pk_fma_f32 v[0:1], v[32:33], v[4:5], v[240:241]
	global_store_dwordx4 v[50:51], v[0:3], off offset:192

;     static DI void run(const f32x4 (&acc)[8][4], const TileCtx& tc, const Params& p, ldsp_t wb) {
;     ...
;             for (int mm = 0; mm < 4; ++mm) { __builtin_amdgcn_sched_barrier(0);
;                 const int m = h * 4 + mm;
;                 const int row = tc.brow + tc.wr * 128 + m * 16 + tc.fr;
;                 float* xr = xrow_ptr(p, row) + col0;
;                 const float* xs = (EK == 1 && tc.l == 0) ? p.x + (size_t)row * DM + col0 : xr;
;                 float part = 0.f;
; #pragma unroll
;                 for (int n = 0; n < 4; ++n) {
;                     f32x4 xv = *(const f32x4*)(xs + n * 16);
;                     xv += gv[n] * acc[m][n];
;                     *(f32x4*)(xr + n * 16) = xv;
.LBB0_238:
	v_add_u32_e32 v32, 0x70, v132
	v_add_u32_e32 v0, 0xffffc070, v132
	s_waitcnt lgkmcnt(0)
	v_ashrrev_i32_e32 v33, 31, v32
	v_cmp_gt_i32_e32 vcc, s33, v32
	v_mov_b32_e32 v2, s71
	v_mov_b32_e32 v3, s55
	v_cndmask_b32_e32 v1, 0, v33, vcc
	v_cndmask_b32_e32 v0, v0, v32, vcc
	v_cndmask_b32_e32 v3, v2, v3, vcc
	v_mov_b32_e32 v2, s70
	v_mov_b32_e32 v34, s54
	v_cndmask_b32_e32 v2, v2, v34, vcc
	v_lshlrev_b64 v[0:1], 12, v[0:1]
	v_lshl_add_u64 v[0:1], v[2:3], 0, v[0:1]
	v_lshl_add_u64 v[34:35], v[176:177], 2, v[0:1]
	s_barrier
	global_load_dwordx4 v[0:3], v[34:35], off
	global_load_dwordx4 v[232:235], v[34:35], off offset:64
	global_load_dwordx4 v[236:239], v[34:35], off offset:128
	global_load_dwordx4 v[240:243], v[34:35], off offset:192
	s_mov_b64 s[4:5], -1
	s_and_b64 vcc, exec, s[36:37]
	s_waitcnt vmcnt(3)
	v_pk_fma_f32 v[26:27], v[26:27], v[30:31], v[2:3]
	v_pk_fma_f32 v[24:25], v[24:25], v[28:29], v[0:1]
	global_store_dwordx4 v[34:35], v[24:27], off
	s_cbranch_vccz .LBB0_240
	s_nop 1
	s_mov_b64 s[4:5], 0
	s_waitcnt vmcnt(3)
	v_pk_fma_f32 v[2:3], v[18:19], v[22:23], v[234:235]
	v_pk_fma_f32 v[0:1], v[16:17], v[20:21], v[232:233]
	global_store_dwordx4 v[34:35], v[0:3], off offset:64
	s_nop 1
	s_waitcnt vmcnt(3)
	v_pk_fma_f32 v[2:3], v[10:11], v[14:15], v[238:239]
	v_pk_fma_f32 v[0:1], v[8:9], v[12:13], v[236:237]
	global_store_dwordx4 v[34:35], v[0:3], off offset:128
	s_nop 1
	s_waitcnt vmcnt(3)
	v_pk_fma_f32 v[2:3], v[70:71], v[6:7], v[242:243]
	v_pk_fma_f32 v[0:1], v[68:69], v[4:5], v[240:241]
	global_store_dwordx4 v[34:35], v[0:3], off offset:192
